# up-proj epilogues: the 15 serialized per-tile QK-norm gain loads hoisted into free VGPRs behind the first one (one wait instead of 16)
# speedup vs baseline: 1.0058x; 1.0019x over previous
; #define SBAR() __builtin_amdgcn_sched_barrier(0)
; DEV int opaque_tid() { int t = threadIdx.x; asm volatile("" : "+v"(t)); return t; }
; DEV void glds16(const u16* g, char* l) { __builtin_amdgcn_global_load_lds((const unsigned*)g, (unsigned*)l, 16, 0, 0); }
; template <int WM, int WN, int BN, int EPI>
; DEV void gemm_tile(const u16* __restrict__ A, int lda, const u16* __restrict__ Bt, int ldb, int K, int m0, char* lds,
;                    const Params& P, int layer, int batch, int nt) {
;     ...
;   const int tid = opaque_tid(), wid = tid >> 6, lane = tid & 63, r32 = lane & 31, hi = lane >> 5;
;   const int wm = wid / WN, wn = wid % WN;
;   char* As = lds; char* Bs = lds + 65536;
;   f32x16 acc[MI][NI];
; #pragma unroll
;   for (int mi = 0; mi < MI; ++mi)
; #pragma unroll
;     for (int ni = 0; ni < NI; ++ni) acc[mi][ni] = f32x16{};
;   const int srow = tid >> 3, sch = (tid & 7) ^ ((srow >> 1) & 7);
;   const u16* Ap = A + (long)(m0 + srow) * lda + sch * 8;
;   const u16* Bp = Bt + (long)srow * ldb + sch * 8;
;   const int soff = tid * 16;
;     ...
;   GLOAD(0, 0); asm volatile("s_waitcnt vmcnt(0)" ::: "memory"); __syncthreads();
;   const int nk = K >> 6;
;   for (int kt = 0; kt < nk; ++kt) {
;     const bool more = kt + 1 < nk;
;     const int nb = (kt + 1) & 1;
;     const char* as = As + (kt & 1) * 32768; const char* bs = Bs + (kt & 1) * 32768;
; #pragma unroll
;     for (int ks = 0; ks < 4; ++ks) {
;       if (more) { glds16(Ap + (long)ks * 64 * lda + (kt + 1) * 64, As + nb * 32768 + soff + ks * 8192);
;                   if (ks < NB) glds16(Bp + (long)ks * 64 * ldb + (kt + 1) * 64, Bs + nb * 32768 + soff + ks * 8192); }
;       SBAR();
;       bf16x8 xf[MI], wf[NI];
; #pragma unroll
;       for (int mi = 0; mi < MI; ++mi) xf[mi] = *reinterpret_cast<const bf16x8*>(as + swz128(wm * (MI * 32) + mi * 32 + r32, ks * 2 + hi));
; #pragma unroll
;       for (int ni = 0; ni < NI; ++ni) wf[ni] = *reinterpret_cast<const bf16x8*>(bs + swz128(wn * (NI * 32) + ni * 32 + r32, ks * 2 + hi));
; #pragma unroll
;       for (int mi = 0; mi < MI; ++mi)
; #pragma unroll
;         for (int ni = 0; ni < NI; ++ni) acc[mi][ni] = __builtin_amdgcn_mfma_f32_32x32x16_bf16(wf[ni], xf[mi], acc[mi][ni], 0, 0, 0);
;     }
;     asm volatile("s_waitcnt vmcnt(0)" ::: "memory");
;     __syncthreads();
;   }
.LBB0_358:
	s_mul_i32 s2, s54, 0xc0
	s_mul_i32 s3, s51, 0x300
	s_add_i32 s3, s2, s3
	s_lshl_b32 s3, s3, 9
	s_add_u32 s60, s36, s3
	s_addc_u32 s61, s38, 0
	s_lshl_b32 s3, s55, 8
	v_mov_b32_e32 v100, v226
	s_and_b32 s3, s3, 0x3f00
	s_add_i32 s22, 0, 0x10000
	v_ashrrev_i32_e32 v0, 3, v100
	v_lshrrev_b32_e32 v1, 4, v100
	v_add_u32_e32 v2, s3, v0
	v_xor_b32_e32 v1, v1, v100
	v_ashrrev_i32_e32 v3, 31, v2
	v_lshlrev_b32_e32 v5, 4, v100
	v_lshlrev_b64 v[2:3], 9, v[2:3]
	v_lshlrev_b32_e32 v1, 4, v1
	v_add_u32_e32 v120, 0, v5
	v_lshl_add_u64 v[2:3], s[6:7], 0, v[2:3]
	v_and_b32_e32 v184, 0x70, v1
	v_readfirstlane_b32 s82, v120
	v_add_u32_e32 v6, 0x2000, v120
	v_lshl_add_u64 v[96:97], v[2:3], 0, v[184:185]
	v_ashrrev_i32_e32 v1, 31, v0
	s_mov_b32 m0, s82
	v_readfirstlane_b32 s79, v6
	v_add_u32_e32 v6, 0x4000, v120
	v_lshlrev_b64 v[0:1], 9, v[0:1]
	global_load_lds_dwordx4 v[96:97], off
	v_lshl_add_u64 v[2:3], v[96:97], 0, s[40:41]
	s_mov_b32 m0, s79
	v_readfirstlane_b32 s65, v6
	v_lshl_add_u64 v[0:1], s[60:61], 0, v[0:1]
	global_load_lds_dwordx4 v[2:3], off
	v_lshl_add_u64 v[2:3], v[96:97], 0, s[28:29]
	s_mov_b32 m0, s65
	s_mov_b64 s[60:61], 0x18000
	v_add_u32_e32 v6, 0x6000, v120
	global_load_lds_dwordx4 v[2:3], off
	v_lshl_add_u64 v[2:3], v[96:97], 0, s[60:61]
	v_readfirstlane_b32 s60, v6
	s_mov_b32 m0, s60
	v_add_u32_e32 v121, s22, v5
	global_load_lds_dwordx4 v[2:3], off
	v_readfirstlane_b32 s81, v121
	v_add_u32_e32 v2, 0x2000, v121
	v_lshl_add_u64 v[98:99], v[0:1], 0, v[184:185]
	s_mov_b32 m0, s81
	v_readfirstlane_b32 s75, v2
	v_add_u32_e32 v2, 0x4000, v121
	global_load_lds_dwordx4 v[98:99], off
	v_lshl_add_u64 v[0:1], v[98:99], 0, s[40:41]
	s_mov_b32 m0, s75
	v_readfirstlane_b32 s61, v2
	v_and_b32_e32 v101, 31, v100
	global_load_lds_dwordx4 v[0:1], off
	v_lshl_add_u64 v[0:1], v[98:99], 0, s[28:29]
	s_mov_b32 m0, s61
	v_add_u32_e32 v5, 0x8000, v120
	v_ashrrev_i32_e32 v103, 6, v100
	global_load_lds_dwordx4 v[0:1], off
	v_lshlrev_b32_e32 v1, 7, v101
	v_add_u32_e32 v6, 0x8000, v121
	v_readfirstlane_b32 s62, v5
	v_lshlrev_b32_e32 v0, 12, v103
	v_add_u32_e32 v124, s22, v1
	v_lshl_add_u64 v[2:3], v[96:97], 0, s[30:31]
	s_mov_b32 m0, s62
	v_readfirstlane_b32 s22, v6
	s_waitcnt vmcnt(0)
	s_waitcnt vmcnt(0) lgkmcnt(0)
	s_barrier
	v_add3_u32 v123, 0, v0, v1
	v_lshl_add_u64 v[0:1], v[98:99], 0, s[30:31]
	global_load_lds_dwordx4 v[2:3], off
	s_mov_b32 m0, s22
	v_lshrrev_b32_e32 v4, 5, v100
	global_load_lds_dwordx4 v[0:1], off
	v_bfe_u32 v102, v100, 5, 1
	v_bfe_u32 v122, v100, 1, 3
	v_bitop3_b32 v0, v4, v122, 1 bitop3:0x6c
	v_lshlrev_b32_e32 v4, 4, v0
	v_add_u32_e32 v104, v124, v4
	ds_read_b128 v[0:3], v104
	v_add_u32_e32 v125, v123, v4
	ds_read_b128 v[16:19], v125
	v_add_u32_e32 v26, 0xa000, v121
	v_lshl_add_u64 v[24:25], v[96:97], 0, s[42:43]
	v_readfirstlane_b32 s63, v26
	s_waitcnt lgkmcnt(0)
	v_mfma_f32_32x32x16_bf16 v[80:95], v[0:3], v[16:19], 0
	ds_read_b128 v[0:3], v104 offset:4096
	ds_read_b128 v[4:7], v104 offset:8192
	s_waitcnt lgkmcnt(0)
	v_mfma_f32_32x32x16_bf16 v[64:79], v[0:3], v[16:19], 0
	v_mfma_f32_32x32x16_bf16 v[48:63], v[4:7], v[16:19], 0
	ds_read_b128 v[0:3], v104 offset:12288
	ds_read_b128 v[4:7], v104 offset:16384
	ds_read_b128 v[20:23], v104 offset:20480
	s_waitcnt lgkmcnt(0)
	v_mfma_f32_32x32x16_bf16 v[32:47], v[0:3], v[16:19], 0
	v_add_u32_e32 v0, 0xa000, v120
	s_nop 0
	v_readfirstlane_b32 s74, v0
	s_mov_b32 m0, s74
	s_nop 0
	global_load_lds_dwordx4 v[24:25], off
	v_lshl_add_u64 v[24:25], v[98:99], 0, s[42:43]
	s_mov_b32 m0, s63
	v_mfma_f32_32x32x16_bf16 v[0:15], v[4:7], v[16:19], 0
	global_load_lds_dwordx4 v[24:25], off
	v_mfma_f32_32x32x16_bf16 v[16:31], v[20:23], v[16:19], 0
	v_bitop3_b32 v105, v102, v122, 2 bitop3:0x36
	v_lshlrev_b32_e32 v110, 4, v105
	v_add_u32_e32 v105, v124, v110
	ds_read_b128 v[106:109], v105
	v_add_u32_e32 v126, v123, v110
	ds_read_b128 v[110:113], v126
	v_add_u32_e32 v127, 0xc000, v120
	s_mov_b64 s[86:87], 0x10080
	v_readfirstlane_b32 s78, v127
	v_lshl_add_u64 v[118:119], v[96:97], 0, s[86:87]
	s_mov_b32 m0, s78
	s_waitcnt lgkmcnt(0)
	v_mfma_f32_32x32x16_bf16 v[80:95], v[106:109], v[110:113], v[80:95]
	ds_read_b128 v[106:109], v105 offset:4096
	ds_read_b128 v[114:117], v105 offset:8192
	s_waitcnt lgkmcnt(0)
	v_mfma_f32_32x32x16_bf16 v[64:79], v[106:109], v[110:113], v[64:79]
	v_mfma_f32_32x32x16_bf16 v[48:63], v[114:117], v[110:113], v[48:63]
	ds_read_b128 v[106:109], v105 offset:12288
	ds_read_b128 v[114:117], v105 offset:16384
	s_waitcnt lgkmcnt(0)
	v_mfma_f32_32x32x16_bf16 v[0:15], v[114:117], v[110:113], v[0:15]
	v_add_u32_e32 v116, 0xc000, v121
	v_lshl_add_u64 v[114:115], v[98:99], 0, s[86:87]
	v_readfirstlane_b32 s64, v116
	v_mfma_f32_32x32x16_bf16 v[32:47], v[106:109], v[110:113], v[32:47]
	ds_read_b128 v[106:109], v105 offset:20480
	global_load_lds_dwordx4 v[118:119], off
	s_mov_b32 m0, s64
	s_nop 0
	global_load_lds_dwordx4 v[114:115], off
	s_waitcnt lgkmcnt(0)
	v_mfma_f32_32x32x16_bf16 v[16:31], v[106:109], v[110:113], v[16:31]
	v_bitop3_b32 v106, v102, v122, 4 bitop3:0x36
	v_lshlrev_b32_e32 v110, 4, v106
	v_add_u32_e32 v118, v124, v110
	ds_read_b128 v[106:109], v118
	v_add_u32_e32 v119, v123, v110
	ds_read_b128 v[110:113], v119
	s_mov_b64 s[86:87], 0x18080
	s_waitcnt lgkmcnt(0)
	v_mfma_f32_32x32x16_bf16 v[80:95], v[106:109], v[110:113], v[80:95]
	ds_read_b128 v[106:109], v118 offset:4096
	ds_read_b128 v[114:117], v118 offset:8192
	s_waitcnt lgkmcnt(0)
	v_mfma_f32_32x32x16_bf16 v[64:79], v[106:109], v[110:113], v[64:79]
	v_mfma_f32_32x32x16_bf16 v[48:63], v[114:117], v[110:113], v[48:63]
	ds_read_b128 v[106:109], v118 offset:12288
	ds_read_b128 v[114:117], v118 offset:16384
	s_waitcnt lgkmcnt(0)
; #define SBAR() __builtin_amdgcn_sched_barrier(0)
; DEV void glds16(const u16* g, char* l) { __builtin_amdgcn_global_load_lds((const unsigned*)g, (unsigned*)l, 16, 0, 0); }
; template <int WM, int WN, int BN, int EPI>
; DEV void gemm_tile(const u16* __restrict__ A, int lda, const u16* __restrict__ Bt, int ldb, int K, int m0, char* lds,
;                    const Params& P, int layer, int batch, int nt) {
;     ...
;   for (int kt = 0; kt < nk; ++kt) {
;     const bool more = kt + 1 < nk;
;     const int nb = (kt + 1) & 1;
;     const char* as = As + (kt & 1) * 32768; const char* bs = Bs + (kt & 1) * 32768;
; #pragma unroll
;     for (int ks = 0; ks < 4; ++ks) {
;       if (more) { glds16(Ap + (long)ks * 64 * lda + (kt + 1) * 64, As + nb * 32768 + soff + ks * 8192);
;                   if (ks < NB) glds16(Bp + (long)ks * 64 * ldb + (kt + 1) * 64, Bs + nb * 32768 + soff + ks * 8192); }
;       SBAR();
;       bf16x8 xf[MI], wf[NI];
; #pragma unroll
;       for (int mi = 0; mi < MI; ++mi) xf[mi] = *reinterpret_cast<const bf16x8*>(as + swz128(wm * (MI * 32) + mi * 32 + r32, ks * 2 + hi));
; #pragma unroll
;       for (int ni = 0; ni < NI; ++ni) wf[ni] = *reinterpret_cast<const bf16x8*>(bs + swz128(wn * (NI * 32) + ni * 32 + r32, ks * 2 + hi));
; #pragma unroll
;       for (int mi = 0; mi < MI; ++mi)
; #pragma unroll
;         for (int ni = 0; ni < NI; ++ni) acc[mi][ni] = __builtin_amdgcn_mfma_f32_32x32x16_bf16(wf[ni], xf[mi], acc[mi][ni], 0, 0, 0);
;     }
;     asm volatile("s_waitcnt vmcnt(0)" ::: "memory");
;     __syncthreads();
;   }
	v_mfma_f32_32x32x16_bf16 v[0:15], v[114:117], v[110:113], v[0:15]
	v_add_u32_e32 v116, 0xe000, v120
	v_lshl_add_u64 v[114:115], v[96:97], 0, s[86:87]
	v_readfirstlane_b32 s80, v116
	s_mov_b32 m0, s80
	v_mfma_f32_32x32x16_bf16 v[32:47], v[106:109], v[110:113], v[32:47]
	ds_read_b128 v[106:109], v118 offset:20480
	global_load_lds_dwordx4 v[114:115], off
	s_waitcnt lgkmcnt(0)
	v_mfma_f32_32x32x16_bf16 v[16:31], v[106:109], v[110:113], v[16:31]
	v_bitop3_b32 v106, v102, v122, 6 bitop3:0x36
	v_lshlrev_b32_e32 v110, 4, v106
	v_add_u32_e32 v124, v124, v110
	ds_read_b128 v[106:109], v124
	v_add_u32_e32 v120, v123, v110
	ds_read_b128 v[110:113], v120
	s_mov_b32 m0, s82
	s_mov_b64 s[82:83], 0x100
	s_waitcnt lgkmcnt(0)
	v_mfma_f32_32x32x16_bf16 v[80:95], v[106:109], v[110:113], v[80:95]
	ds_read_b128 v[106:109], v124 offset:4096
	ds_read_b128 v[114:117], v124 offset:8192
	s_waitcnt lgkmcnt(0)
	v_mfma_f32_32x32x16_bf16 v[64:79], v[106:109], v[110:113], v[64:79]
	v_mfma_f32_32x32x16_bf16 v[48:63], v[114:117], v[110:113], v[48:63]
	ds_read_b128 v[106:109], v124 offset:12288
	ds_read_b128 v[114:117], v124 offset:16384
	s_waitcnt lgkmcnt(0)
	v_mfma_f32_32x32x16_bf16 v[0:15], v[114:117], v[110:113], v[0:15]
	v_lshl_add_u64 v[116:117], v[96:97], 0, s[82:83]
	v_lshl_add_u64 v[114:115], v[98:99], 0, s[82:83]
	v_mfma_f32_32x32x16_bf16 v[32:47], v[106:109], v[110:113], v[32:47]
	ds_read_b128 v[106:109], v124 offset:20480
	s_waitcnt vmcnt(0)
	s_waitcnt vmcnt(0) lgkmcnt(0)
	s_barrier
	global_load_lds_dwordx4 v[116:117], off
	s_mov_b32 m0, s81
	v_mfma_f32_32x32x16_bf16 v[16:31], v[106:109], v[110:113], v[16:31]
	global_load_lds_dwordx4 v[114:115], off
	ds_read_b128 v[106:109], v104 offset:32768
	ds_read_b128 v[110:113], v125 offset:32768
	s_mov_b64 s[82:83], 0x8100
	s_mov_b32 m0, s79
	s_waitcnt lgkmcnt(0)
	v_mfma_f32_32x32x16_bf16 v[80:95], v[106:109], v[110:113], v[80:95]
	ds_read_b128 v[106:109], v104 offset:36864
	ds_read_b128 v[114:117], v104 offset:40960
	s_waitcnt lgkmcnt(0)
	v_mfma_f32_32x32x16_bf16 v[64:79], v[106:109], v[110:113], v[64:79]
	v_mfma_f32_32x32x16_bf16 v[48:63], v[114:117], v[110:113], v[48:63]
	ds_read_b128 v[106:109], v104 offset:45056
	ds_read_b128 v[114:117], v104 offset:49152
	s_waitcnt lgkmcnt(0)
	v_mfma_f32_32x32x16_bf16 v[0:15], v[114:117], v[110:113], v[0:15]
	v_lshl_add_u64 v[114:115], v[96:97], 0, s[82:83]
	v_mfma_f32_32x32x16_bf16 v[32:47], v[106:109], v[110:113], v[32:47]
	ds_read_b128 v[106:109], v104 offset:53248
	global_load_lds_dwordx4 v[114:115], off
	v_lshl_add_u64 v[114:115], v[98:99], 0, s[82:83]
	s_mov_b32 m0, s75
	s_nop 0
	global_load_lds_dwordx4 v[114:115], off
	s_waitcnt lgkmcnt(0)
	v_mfma_f32_32x32x16_bf16 v[16:31], v[106:109], v[110:113], v[16:31]
	ds_read_b128 v[106:109], v105 offset:32768
	ds_read_b128 v[110:113], v126 offset:32768
	s_mov_b64 s[82:83], 0x10100
	s_mov_b32 m0, s65
	s_waitcnt lgkmcnt(0)
	v_mfma_f32_32x32x16_bf16 v[80:95], v[106:109], v[110:113], v[80:95]
	ds_read_b128 v[106:109], v105 offset:36864
	ds_read_b128 v[114:117], v105 offset:40960
	s_waitcnt lgkmcnt(0)
	v_mfma_f32_32x32x16_bf16 v[64:79], v[106:109], v[110:113], v[64:79]
	v_mfma_f32_32x32x16_bf16 v[48:63], v[114:117], v[110:113], v[48:63]
	ds_read_b128 v[106:109], v105 offset:45056
	ds_read_b128 v[114:117], v105 offset:49152
	s_waitcnt lgkmcnt(0)
	v_mfma_f32_32x32x16_bf16 v[0:15], v[114:117], v[110:113], v[0:15]
	v_lshl_add_u64 v[114:115], v[96:97], 0, s[82:83]
	v_mfma_f32_32x32x16_bf16 v[32:47], v[106:109], v[110:113], v[32:47]
	ds_read_b128 v[106:109], v105 offset:53248
	global_load_lds_dwordx4 v[114:115], off
	v_lshl_add_u64 v[114:115], v[98:99], 0, s[82:83]
	s_mov_b32 m0, s61
	s_nop 0
	global_load_lds_dwordx4 v[114:115], off
	s_waitcnt lgkmcnt(0)
	v_mfma_f32_32x32x16_bf16 v[16:31], v[106:109], v[110:113], v[16:31]
	ds_read_b128 v[106:109], v118 offset:32768
	ds_read_b128 v[110:113], v119 offset:32768
	s_mov_b32 m0, s60
	s_mov_b64 s[60:61], 0x18100
	s_waitcnt lgkmcnt(0)
	v_mfma_f32_32x32x16_bf16 v[80:95], v[106:109], v[110:113], v[80:95]
	ds_read_b128 v[106:109], v118 offset:36864
	ds_read_b128 v[114:117], v118 offset:40960
	s_waitcnt lgkmcnt(0)
	v_mfma_f32_32x32x16_bf16 v[64:79], v[106:109], v[110:113], v[64:79]
	v_mfma_f32_32x32x16_bf16 v[48:63], v[114:117], v[110:113], v[48:63]
	ds_read_b128 v[106:109], v118 offset:45056
	ds_read_b128 v[114:117], v118 offset:49152
	s_waitcnt lgkmcnt(0)
	v_mfma_f32_32x32x16_bf16 v[0:15], v[114:117], v[110:113], v[0:15]
	v_lshl_add_u64 v[114:115], v[96:97], 0, s[60:61]
	v_mfma_f32_32x32x16_bf16 v[32:47], v[106:109], v[110:113], v[32:47]
	ds_read_b128 v[106:109], v118 offset:53248
	global_load_lds_dwordx4 v[114:115], off
	s_waitcnt lgkmcnt(0)
	v_mfma_f32_32x32x16_bf16 v[16:31], v[106:109], v[110:113], v[16:31]
	ds_read_b128 v[106:109], v124 offset:32768
	ds_read_b128 v[110:113], v120 offset:32768
	s_mov_b64 s[60:61], 0x180
	s_mov_b32 m0, s62
	s_waitcnt lgkmcnt(0)
	v_mfma_f32_32x32x16_bf16 v[80:95], v[106:109], v[110:113], v[80:95]
	ds_read_b128 v[106:109], v124 offset:36864
	ds_read_b128 v[114:117], v124 offset:40960
	s_waitcnt lgkmcnt(0)
	v_mfma_f32_32x32x16_bf16 v[64:79], v[106:109], v[110:113], v[64:79]
	v_mfma_f32_32x32x16_bf16 v[48:63], v[114:117], v[110:113], v[48:63]
	ds_read_b128 v[106:109], v124 offset:45056
	ds_read_b128 v[114:117], v124 offset:49152
	s_waitcnt lgkmcnt(0)
	v_mfma_f32_32x32x16_bf16 v[0:15], v[114:117], v[110:113], v[0:15]
	v_lshl_add_u64 v[116:117], v[96:97], 0, s[60:61]
	v_lshl_add_u64 v[114:115], v[98:99], 0, s[60:61]
	v_mfma_f32_32x32x16_bf16 v[32:47], v[106:109], v[110:113], v[32:47]
	ds_read_b128 v[106:109], v124 offset:53248
	s_waitcnt vmcnt(0)
	s_waitcnt vmcnt(0) lgkmcnt(0)
	s_barrier
; #define SBAR() __builtin_amdgcn_sched_barrier(0)
; DEV void glds16(const u16* g, char* l) { __builtin_amdgcn_global_load_lds((const unsigned*)g, (unsigned*)l, 16, 0, 0); }
; DEV void epi_uq(f32x16 (&acc)[1][6], const Params& P, int layer, int batch, int m0, int head, int wid, int r32, int hi, char* lds) {
;   const int t = m0 + wid * 32 + r32;
; template <int WM, int WN, int BN, int EPI>
; DEV void gemm_tile(const u16* __restrict__ A, int lda, const u16* __restrict__ Bt, int ldb, int K, int m0, char* lds,
;                    const Params& P, int layer, int batch, int nt) {
;     ...
;   for (int kt = 0; kt < nk; ++kt) {
;     const bool more = kt + 1 < nk;
;     const int nb = (kt + 1) & 1;
;     const char* as = As + (kt & 1) * 32768; const char* bs = Bs + (kt & 1) * 32768;
; #pragma unroll
;     for (int ks = 0; ks < 4; ++ks) {
;       if (more) { glds16(Ap + (long)ks * 64 * lda + (kt + 1) * 64, As + nb * 32768 + soff + ks * 8192);
;                   if (ks < NB) glds16(Bp + (long)ks * 64 * ldb + (kt + 1) * 64, Bs + nb * 32768 + soff + ks * 8192); }
;       SBAR();
;       bf16x8 xf[MI], wf[NI];
; #pragma unroll
;       for (int mi = 0; mi < MI; ++mi) xf[mi] = *reinterpret_cast<const bf16x8*>(as + swz128(wm * (MI * 32) + mi * 32 + r32, ks * 2 + hi));
; #pragma unroll
;       for (int ni = 0; ni < NI; ++ni) wf[ni] = *reinterpret_cast<const bf16x8*>(bs + swz128(wn * (NI * 32) + ni * 32 + r32, ks * 2 + hi));
; #pragma unroll
;       for (int mi = 0; mi < MI; ++mi)
; #pragma unroll
;         for (int ni = 0; ni < NI; ++ni) acc[mi][ni] = __builtin_amdgcn_mfma_f32_32x32x16_bf16(wf[ni], xf[mi], acc[mi][ni], 0, 0, 0);
;     }
;     asm volatile("s_waitcnt vmcnt(0)" ::: "memory");
;     __syncthreads();
;   }
	global_load_lds_dwordx4 v[116:117], off
	s_mov_b32 m0, s22
	v_mfma_f32_32x32x16_bf16 v[16:31], v[106:109], v[110:113], v[16:31]
	global_load_lds_dwordx4 v[114:115], off
	ds_read_b128 v[106:109], v104
	ds_read_b128 v[110:113], v125
	s_mov_b64 s[60:61], 0x8180
	s_mov_b32 m0, s74
	s_waitcnt lgkmcnt(0)
	v_mfma_f32_32x32x16_bf16 v[80:95], v[106:109], v[110:113], v[80:95]
	ds_read_b128 v[106:109], v104 offset:4096
	ds_read_b128 v[114:117], v104 offset:8192
	s_waitcnt lgkmcnt(0)
	v_mfma_f32_32x32x16_bf16 v[64:79], v[106:109], v[110:113], v[64:79]
	v_mfma_f32_32x32x16_bf16 v[48:63], v[114:117], v[110:113], v[48:63]
	ds_read_b128 v[106:109], v104 offset:12288
	ds_read_b128 v[114:117], v104 offset:16384
	s_waitcnt lgkmcnt(0)
	v_mfma_f32_32x32x16_bf16 v[0:15], v[114:117], v[110:113], v[0:15]
	v_lshl_add_u64 v[114:115], v[96:97], 0, s[60:61]
	v_mfma_f32_32x32x16_bf16 v[32:47], v[106:109], v[110:113], v[32:47]
	ds_read_b128 v[106:109], v104 offset:20480
	global_load_lds_dwordx4 v[114:115], off
	v_lshl_add_u64 v[114:115], v[98:99], 0, s[60:61]
	s_mov_b32 m0, s63
	s_nop 0
	global_load_lds_dwordx4 v[114:115], off
	s_waitcnt lgkmcnt(0)
	v_mfma_f32_32x32x16_bf16 v[16:31], v[106:109], v[110:113], v[16:31]
	ds_read_b128 v[106:109], v105
	ds_read_b128 v[110:113], v126
	s_mov_b64 s[60:61], 0x10180
	s_mov_b32 m0, s78
	v_lshl_add_u64 v[98:99], v[98:99], 0, s[60:61]
	s_waitcnt lgkmcnt(0)
	v_mfma_f32_32x32x16_bf16 v[80:95], v[106:109], v[110:113], v[80:95]
	ds_read_b128 v[106:109], v105 offset:4096
	ds_read_b128 v[114:117], v105 offset:8192
	s_waitcnt lgkmcnt(0)
	v_mfma_f32_32x32x16_bf16 v[64:79], v[106:109], v[110:113], v[64:79]
	v_mfma_f32_32x32x16_bf16 v[48:63], v[114:117], v[110:113], v[48:63]
	ds_read_b128 v[106:109], v105 offset:12288
	ds_read_b128 v[114:117], v105 offset:16384
	s_waitcnt lgkmcnt(0)
	v_mfma_f32_32x32x16_bf16 v[0:15], v[114:117], v[110:113], v[0:15]
	v_lshl_add_u64 v[114:115], v[96:97], 0, s[60:61]
	v_mfma_f32_32x32x16_bf16 v[32:47], v[106:109], v[110:113], v[32:47]
	ds_read_b128 v[106:109], v105 offset:20480
	global_load_lds_dwordx4 v[114:115], off
	s_mov_b32 m0, s64
	s_nop 0
	global_load_lds_dwordx4 v[98:99], off
	s_waitcnt lgkmcnt(0)
	v_mfma_f32_32x32x16_bf16 v[16:31], v[106:109], v[110:113], v[16:31]
	ds_read_b128 v[106:109], v118
	ds_read_b128 v[110:113], v119
	s_mov_b64 s[60:61], 0x18180
	s_mov_b32 m0, s80
	v_lshl_add_u64 v[96:97], v[96:97], 0, s[60:61]
	s_waitcnt lgkmcnt(0)
	v_mfma_f32_32x32x16_bf16 v[80:95], v[106:109], v[110:113], v[80:95]
	ds_read_b128 v[106:109], v118 offset:4096
	ds_read_b128 v[114:117], v118 offset:8192
	s_waitcnt lgkmcnt(0)
	v_mfma_f32_32x32x16_bf16 v[64:79], v[106:109], v[110:113], v[64:79]
	v_mfma_f32_32x32x16_bf16 v[48:63], v[114:117], v[110:113], v[48:63]
	ds_read_b128 v[106:109], v118 offset:12288
	ds_read_b128 v[114:117], v118 offset:16384
	s_waitcnt lgkmcnt(0)
	v_mfma_f32_32x32x16_bf16 v[32:47], v[106:109], v[110:113], v[32:47]
	ds_read_b128 v[106:109], v118 offset:20480
	global_load_lds_dwordx4 v[96:97], off
	v_mfma_f32_32x32x16_bf16 v[0:15], v[114:117], v[110:113], v[0:15]
	s_waitcnt lgkmcnt(0)
	v_mfma_f32_32x32x16_bf16 v[16:31], v[106:109], v[110:113], v[16:31]
	ds_read_b128 v[96:99], v124
	ds_read_b128 v[106:109], v120
	s_waitcnt lgkmcnt(0)
	v_mfma_f32_32x32x16_bf16 v[80:95], v[96:99], v[106:109], v[80:95]
	ds_read_b128 v[96:99], v124 offset:4096
	s_waitcnt lgkmcnt(0)
	v_mfma_f32_32x32x16_bf16 v[64:79], v[96:99], v[106:109], v[64:79]
	ds_read_b128 v[96:99], v124 offset:8192
	s_waitcnt lgkmcnt(0)
	v_mfma_f32_32x32x16_bf16 v[48:63], v[96:99], v[106:109], v[48:63]
	ds_read_b128 v[96:99], v124 offset:12288
	s_waitcnt lgkmcnt(0)
	v_mfma_f32_32x32x16_bf16 v[32:47], v[96:99], v[106:109], v[32:47]
	ds_read_b128 v[96:99], v124 offset:16384
	s_waitcnt lgkmcnt(0)
	v_mfma_f32_32x32x16_bf16 v[0:15], v[96:99], v[106:109], v[0:15]
	ds_read_b128 v[96:99], v124 offset:20480
	s_waitcnt vmcnt(0)
	s_waitcnt vmcnt(0) lgkmcnt(0)
	s_barrier
	v_mfma_f32_32x32x16_bf16 v[16:31], v[96:99], v[106:109], v[16:31]
	ds_read_b128 v[96:99], v104 offset:32768
	ds_read_b128 v[106:109], v125 offset:32768
	s_waitcnt lgkmcnt(0)
	v_mfma_f32_32x32x16_bf16 v[80:95], v[96:99], v[106:109], v[80:95]
	ds_read_b128 v[96:99], v104 offset:36864
	s_waitcnt lgkmcnt(0)
	v_mfma_f32_32x32x16_bf16 v[64:79], v[96:99], v[106:109], v[64:79]
	ds_read_b128 v[96:99], v104 offset:40960
	s_waitcnt lgkmcnt(0)
	v_mfma_f32_32x32x16_bf16 v[48:63], v[96:99], v[106:109], v[48:63]
	ds_read_b128 v[96:99], v104 offset:45056
	s_waitcnt lgkmcnt(0)
	v_mfma_f32_32x32x16_bf16 v[32:47], v[96:99], v[106:109], v[32:47]
	ds_read_b128 v[96:99], v104 offset:49152
	s_waitcnt lgkmcnt(0)
	v_mfma_f32_32x32x16_bf16 v[0:15], v[96:99], v[106:109], v[0:15]
	ds_read_b128 v[96:99], v104 offset:53248
	s_waitcnt lgkmcnt(0)
	v_mfma_f32_32x32x16_bf16 v[16:31], v[96:99], v[106:109], v[16:31]
	ds_read_b128 v[96:99], v105 offset:32768
	ds_read_b128 v[106:109], v126 offset:32768
	s_waitcnt lgkmcnt(0)
	v_mfma_f32_32x32x16_bf16 v[80:95], v[96:99], v[106:109], v[80:95]
	ds_read_b128 v[96:99], v105 offset:36864
	s_waitcnt lgkmcnt(0)
	v_mfma_f32_32x32x16_bf16 v[64:79], v[96:99], v[106:109], v[64:79]
	ds_read_b128 v[96:99], v105 offset:40960
	s_waitcnt lgkmcnt(0)
	v_mfma_f32_32x32x16_bf16 v[48:63], v[96:99], v[106:109], v[48:63]
	ds_read_b128 v[96:99], v105 offset:45056
	s_waitcnt lgkmcnt(0)
	v_mfma_f32_32x32x16_bf16 v[32:47], v[96:99], v[106:109], v[32:47]
	ds_read_b128 v[96:99], v105 offset:49152
	s_waitcnt lgkmcnt(0)
	v_mfma_f32_32x32x16_bf16 v[0:15], v[96:99], v[106:109], v[0:15]
	ds_read_b128 v[96:99], v105 offset:53248
	s_waitcnt lgkmcnt(0)
	v_mfma_f32_32x32x16_bf16 v[16:31], v[96:99], v[106:109], v[16:31]
	ds_read_b128 v[96:99], v118 offset:32768
	ds_read_b128 v[104:107], v119 offset:32768
	s_waitcnt lgkmcnt(0)
	v_mfma_f32_32x32x16_bf16 v[80:95], v[96:99], v[104:107], v[80:95]
	ds_read_b128 v[96:99], v118 offset:36864
	s_waitcnt lgkmcnt(0)
	v_mfma_f32_32x32x16_bf16 v[64:79], v[96:99], v[104:107], v[64:79]
	ds_read_b128 v[96:99], v118 offset:40960
	s_waitcnt lgkmcnt(0)
	v_mfma_f32_32x32x16_bf16 v[48:63], v[96:99], v[104:107], v[48:63]
	ds_read_b128 v[96:99], v118 offset:45056
	s_waitcnt lgkmcnt(0)
	v_mfma_f32_32x32x16_bf16 v[32:47], v[96:99], v[104:107], v[32:47]
	ds_read_b128 v[96:99], v118 offset:49152
	s_waitcnt lgkmcnt(0)
	v_mfma_f32_32x32x16_bf16 v[0:15], v[96:99], v[104:107], v[0:15]
	ds_read_b128 v[96:99], v118 offset:53248
	s_waitcnt lgkmcnt(0)
	v_mfma_f32_32x32x16_bf16 v[16:31], v[96:99], v[104:107], v[16:31]
	ds_read_b128 v[96:99], v124 offset:32768
	ds_read_b128 v[104:107], v120 offset:32768
	ds_read_b128 v[108:111], v124 offset:36864
	ds_read_b128 v[112:115], v124 offset:40960
	ds_read_b128 v[116:119], v124 offset:45056
	ds_read_b128 v[120:123], v124 offset:49152
	ds_read_b128 v[124:127], v124 offset:53248
	s_waitcnt vmcnt(0)
	s_waitcnt lgkmcnt(5)
	v_mfma_f32_32x32x16_bf16 v[80:95], v[96:99], v[104:107], v[80:95]
	v_lshl_add_u32 v99, v103, 5, s3
	v_or_b32_e32 v96, v99, v101
	v_ashrrev_i32_e32 v97, 31, v96
	s_mov_b32 s3, 0x20000
	s_waitcnt lgkmcnt(0)
	s_barrier
; DEV void epi_uq(f32x16 (&acc)[1][6], const Params& P, int layer, int batch, int m0, int head, int wid, int r32, int hi, char* lds) {
;   const int t = m0 + wid * 32 + r32;
;   const float rc = __builtin_amdgcn_rsqf((WS{P.ws}.ssq_cq()[t] + WS{P.ws}.ssq_cq()[TB + t] + WS{P.ws}.ssq_cq()[2 * TB + t] + WS{P.ws}.ssq_cq()[3 * TB + t]) * (1.f / 256.f) + EPS);
;   float s = 0.f;
; #pragma unroll
;   for (int ni = 0; ni < 6; ++ni)
; #pragma unroll
;     for (int r = 0; r < 16; ++r) { acc[0][ni][r] *= rc; s += acc[0][ni][r] * acc[0][ni][r]; }
;   s = swapsum(s);
;   constexpr float SCQ = 0.07216878364870323f * LOG2E;
;   const float inv = __builtin_amdgcn_rsqf(s * (1.f / 192.f) + EPS) * SCQ;
;   const float* g = WS{P.ws}.consts() + layer * 1024 + 320;
;   char* slab = lds + wid * 12800; char* dst = slab + r32 * 400;
; #pragma unroll
;   for (int ni = 0; ni < 4; ++ni)
; #pragma unroll
;     for (int r4 = 0; r4 < 4; ++r4) {
;       const int c = ni * 32 + r4 * 8 + hi * 4;
;       const float4 gg = *reinterpret_cast<const float4*>(g + c);
;       const f32x16& a = acc[0][ni];
;       st4lds(dst, c, a[r4 * 4] * inv * gg.x, a[r4 * 4 + 1] * inv * gg.y, a[r4 * 4 + 2] * inv * gg.z, a[r4 * 4 + 3] * inv * gg.w);
	v_mfma_f32_32x32x16_bf16 v[64:79], v[108:111], v[104:107], v[64:79]
	v_lshl_add_u64 v[108:109], v[96:97], 2, s[8:9]
	v_add_co_u32_e32 v110, vcc, s93, v108
	v_lshlrev_b32_e32 v184, 4, v102
	s_nop 0
	v_addc_co_u32_e32 v111, vcc, 0, v109, vcc
	s_lshl_b32 s22, s2, 1
	v_mfma_f32_32x32x16_bf16 v[48:63], v[112:115], v[104:107], v[48:63]
	v_add_co_u32_e32 v112, vcc, s3, v108
	s_mov_b32 s3, 0x30000
	s_nop 0
	v_addc_co_u32_e32 v113, vcc, 0, v109, vcc
	v_add_co_u32_e32 v114, vcc, s3, v108
	v_mfma_f32_32x32x16_bf16 v[32:47], v[116:119], v[104:107], v[32:47]
	s_nop 0
	v_addc_co_u32_e32 v115, vcc, 0, v109, vcc
	flat_load_dword v97, v[108:109]
	flat_load_dword v98, v[110:111]
	s_nop 0
	flat_load_dword v108, v[112:113]
	flat_load_dword v109, v[114:115]
	s_movk_i32 s3, 0xfff
	s_waitcnt vmcnt(0) lgkmcnt(0)
	v_add_f32_e32 v97, v97, v98
	v_add_f32_e32 v97, v97, v108
	v_add_f32_e32 v97, v97, v109
	v_fmamk_f32 v97, v97, 0x3b800000, v227
	v_rsq_f32_e32 v98, v97
	v_mfma_f32_32x32x16_bf16 v[0:15], v[120:123], v[104:107], v[0:15]
	v_mul_f32_e32 v108, v81, v98
	v_mul_f32_e32 v97, v80, v98
	v_mul_f32_e32 v113, v86, v98
	v_mul_f32_e32 v86, v108, v108
	v_mul_f32_e32 v109, v82, v98
	v_fmac_f32_e32 v86, v97, v97
	v_mul_f32_e32 v110, v83, v98
	v_fmac_f32_e32 v86, v109, v109
	v_mul_f32_e32 v111, v84, v98
	v_fmac_f32_e32 v86, v110, v110
	v_mul_f32_e32 v112, v85, v98
	v_fmac_f32_e32 v86, v111, v111
	v_fmac_f32_e32 v86, v112, v112
	v_mul_f32_e32 v114, v87, v98
	v_fmac_f32_e32 v86, v113, v113
	v_mul_f32_e32 v115, v88, v98
	v_fmac_f32_e32 v86, v114, v114
	v_mul_f32_e32 v116, v89, v98
	v_fmac_f32_e32 v86, v115, v115
	v_mul_f32_e32 v117, v90, v98
	v_fmac_f32_e32 v86, v116, v116
	v_mul_f32_e32 v118, v91, v98
	v_fmac_f32_e32 v86, v117, v117
	v_mul_f32_e32 v119, v92, v98
	v_fmac_f32_e32 v86, v118, v118
	v_mul_f32_e32 v120, v93, v98
	v_fmac_f32_e32 v86, v119, v119
	v_mul_f32_e32 v121, v94, v98
	v_fmac_f32_e32 v86, v120, v120
	v_mul_f32_e32 v122, v95, v98
	v_fmac_f32_e32 v86, v121, v121
	v_mul_f32_e32 v123, v64, v98
	v_fmac_f32_e32 v86, v122, v122
	v_mfma_f32_32x32x16_bf16 v[16:31], v[124:127], v[104:107], v[16:31]
	v_mul_f32_e32 v124, v65, v98
	v_fmac_f32_e32 v86, v123, v123
	v_mul_f32_e32 v125, v66, v98
	v_fmac_f32_e32 v86, v124, v124
	v_mul_f32_e32 v126, v67, v98
	v_fmac_f32_e32 v86, v125, v125
	v_mul_f32_e32 v127, v68, v98
	v_fmac_f32_e32 v86, v126, v126
	v_mul_f32_e32 v128, v69, v98
	v_fmac_f32_e32 v86, v127, v127
	v_mul_f32_e32 v129, v70, v98
	v_fmac_f32_e32 v86, v128, v128
	v_mul_f32_e32 v130, v71, v98
	v_fmac_f32_e32 v86, v129, v129
	v_mul_f32_e32 v80, v72, v98
	v_fmac_f32_e32 v86, v130, v130
	v_mul_f32_e32 v81, v73, v98
	v_fmac_f32_e32 v86, v80, v80
	v_mul_f32_e32 v82, v74, v98
	v_fmac_f32_e32 v86, v81, v81
	v_mul_f32_e32 v83, v75, v98
	v_fmac_f32_e32 v86, v82, v82
	v_mul_f32_e32 v72, v76, v98
	v_fmac_f32_e32 v86, v83, v83
	v_mul_f32_e32 v73, v77, v98
	v_fmac_f32_e32 v86, v72, v72
	v_mul_f32_e32 v74, v78, v98
	v_fmac_f32_e32 v86, v73, v73
	v_mul_f32_e32 v75, v79, v98
	v_fmac_f32_e32 v86, v74, v74
	v_mul_f32_e32 v131, v36, v98
	v_mul_f32_e32 v132, v37, v98
	v_lshl_add_u64 v[36:37], s[10:11], 0, v[184:185]
	v_mul_f32_e32 v68, v48, v98
	v_mul_f32_e32 v70, v50, v98
	v_mul_f32_e32 v71, v51, v98
	v_mul_f32_e32 v66, v54, v98
	v_mul_f32_e32 v67, v55, v98
	v_mul_f32_e32 v54, v56, v98
	v_mul_f32_e32 v55, v57, v98
	v_mul_f32_e32 v56, v58, v98
	v_mul_f32_e32 v57, v59, v98
	v_mul_f32_e32 v50, v60, v98
	v_mul_f32_e32 v51, v61, v98
	v_fmac_f32_e32 v86, v75, v75
	flat_load_dwordx4 v[58:61], v[36:37] offset:1280
	global_load_dwordx4 v[194:197], v[36:37], off offset:1312
	global_load_dwordx4 v[198:201], v[36:37], off offset:1344
	global_load_dwordx4 v[202:205], v[36:37], off offset:1376
	global_load_dwordx4 v[206:209], v[36:37], off offset:1408
	global_load_dwordx4 v[210:213], v[36:37], off offset:1440
	global_load_dwordx4 v[214:217], v[36:37], off offset:1472
	global_load_dwordx4 v[218:221], v[36:37], off offset:1504
	global_load_dwordx4 v[222:225], v[36:37], off offset:1536
	global_load_dwordx4 v[232:235], v[36:37], off offset:1568
	global_load_dwordx4 v[236:239], v[36:37], off offset:1600
	global_load_dwordx4 v[240:243], v[36:37], off offset:1632
	global_load_dwordx4 v[244:247], v[36:37], off offset:1664
	global_load_dwordx4 v[248:251], v[36:37], off offset:1696
	global_load_dwordx4 v[170:173], v[36:37], off offset:1728
	global_load_dwordx4 v[174:177], v[36:37], off offset:1760
	v_mul_f32_e32 v69, v49, v98
	v_fmac_f32_e32 v86, v68, v68
	v_fmac_f32_e32 v86, v69, v69
	v_fmac_f32_e32 v86, v70, v70
	v_mul_f32_e32 v64, v52, v98
	v_fmac_f32_e32 v86, v71, v71
	v_mul_f32_e32 v65, v53, v98
	v_fmac_f32_e32 v86, v64, v64
	v_fmac_f32_e32 v86, v65, v65
	v_fmac_f32_e32 v86, v66, v66
	v_fmac_f32_e32 v86, v67, v67
	v_fmac_f32_e32 v86, v54, v54
	v_fmac_f32_e32 v86, v55, v55
	v_fmac_f32_e32 v86, v56, v56
	v_fmac_f32_e32 v86, v57, v57
	v_fmac_f32_e32 v86, v50, v50
	v_mul_f32_e32 v52, v62, v98
	v_fmac_f32_e32 v86, v51, v51
	v_mul_f32_e32 v53, v63, v98
	v_fmac_f32_e32 v86, v52, v52
	v_mul_f32_e32 v48, v32, v98
	v_fmac_f32_e32 v86, v53, v53
	v_mul_f32_e32 v33, v33, v98
	v_fmac_f32_e32 v86, v48, v48
	v_mul_f32_e32 v49, v34, v98
	v_fmac_f32_e32 v86, v33, v33
	v_mul_f32_e32 v35, v35, v98
	v_fmac_f32_e32 v86, v49, v49
	v_fmac_f32_e32 v86, v35, v35
	v_fmac_f32_e32 v86, v131, v131
	v_fmac_f32_e32 v86, v132, v132
	v_mul_f32_e32 v133, v38, v98
	v_fmac_f32_e32 v86, v133, v133
	v_mul_f32_e32 v134, v39, v98
	v_fmac_f32_e32 v86, v134, v134
	v_mul_f32_e32 v135, v40, v98
	v_fmac_f32_e32 v86, v135, v135
	v_mul_f32_e32 v136, v41, v98
	v_fmac_f32_e32 v86, v136, v136
	v_mul_f32_e32 v137, v42, v98
	v_fmac_f32_e32 v86, v137, v137
; DEV void epi_uq(f32x16 (&acc)[1][6], const Params& P, int layer, int batch, int m0, int head, int wid, int r32, int hi, char* lds) {
;     ...
;   s = swapsum(s);
;   constexpr float SCQ = 0.07216878364870323f * LOG2E;
;   const float inv = __builtin_amdgcn_rsqf(s * (1.f / 192.f) + EPS) * SCQ;
;   const float* g = WS{P.ws}.consts() + layer * 1024 + 320;
;   char* slab = lds + wid * 12800; char* dst = slab + r32 * 400;
; #pragma unroll
;   for (int ni = 0; ni < 4; ++ni)
; #pragma unroll
;     for (int r4 = 0; r4 < 4; ++r4) {
;       const int c = ni * 32 + r4 * 8 + hi * 4;
;       const float4 gg = *reinterpret_cast<const float4*>(g + c);
;       const f32x16& a = acc[0][ni];
;       st4lds(dst, c, a[r4 * 4] * inv * gg.x, a[r4 * 4 + 1] * inv * gg.y, a[r4 * 4 + 2] * inv * gg.z, a[r4 * 4 + 3] * inv * gg.w);
	v_mul_f32_e32 v138, v43, v98
	v_fmac_f32_e32 v86, v138, v138
	v_mul_f32_e32 v139, v44, v98
	v_fmac_f32_e32 v86, v139, v139
	v_mul_f32_e32 v140, v45, v98
	v_mul_f32_e32 v34, v14, v98
	v_mul_lo_u32 v14, v103, s99
	v_fmac_f32_e32 v86, v140, v140
	v_mul_f32_e32 v141, v46, v98
	v_mul_f32_e32 v32, v15, v98
	v_add_u32_e32 v46, 0, v14
	v_mov_b32_e32 v14, v2
	v_mov_b32_e32 v15, v18
	v_mov_b32_e32 v18, v3
	v_mov_b32_e32 v2, v0
	v_mov_b32_e32 v3, v16
	v_fmac_f32_e32 v86, v141, v141
	v_mul_f32_e32 v47, v47, v98
	v_pk_mul_f32 v[42:43], v[2:3], v[98:99] op_sel_hi:[1,0]
	v_mov_b32_e32 v16, v1
	v_fmac_f32_e32 v86, v47, v47
	v_pk_mul_f32 v[84:85], v[42:43], v[42:43]
	v_pk_mul_f32 v[44:45], v[16:17], v[98:99] op_sel_hi:[1,0]
	v_pk_mul_f32 v[14:15], v[14:15], v[98:99] op_sel_hi:[1,0]
	v_add_f32_e32 v0, v84, v86
	v_pk_mul_f32 v[86:87], v[44:45], v[44:45]
	v_pk_mul_f32 v[76:77], v[14:15], v[14:15]
	v_pk_mul_f32 v[40:41], v[18:19], v[98:99] op_sel_hi:[1,0]
	v_add_f32_e32 v0, v86, v0
	v_pk_mul_f32 v[78:79], v[40:41], v[40:41]
	v_add_f32_e32 v0, v76, v0
	v_add_f32_e32 v16, v78, v0
	v_mov_b32_e32 v0, v6
	v_mov_b32_e32 v1, v22
	v_mov_b32_e32 v22, v7
	v_mov_b32_e32 v6, v4
	v_mov_b32_e32 v7, v20
	v_pk_mul_f32 v[6:7], v[6:7], v[98:99] op_sel_hi:[1,0]
	v_mov_b32_e32 v20, v5
	v_pk_mul_f32 v[92:93], v[6:7], v[6:7]
	v_pk_mul_f32 v[4:5], v[20:21], v[98:99] op_sel_hi:[1,0]
	v_pk_mul_f32 v[0:1], v[0:1], v[98:99] op_sel_hi:[1,0]
	v_add_f32_e32 v16, v92, v16
	v_pk_mul_f32 v[20:21], v[4:5], v[4:5]
	v_pk_mul_f32 v[88:89], v[0:1], v[0:1]
	v_pk_mul_f32 v[2:3], v[22:23], v[98:99] op_sel_hi:[1,0]
	v_add_f32_e32 v16, v20, v16
	v_pk_mul_f32 v[90:91], v[2:3], v[2:3]
	v_add_f32_e32 v16, v88, v16
	v_add_f32_e32 v18, v90, v16
	v_mov_b32_e32 v16, v10
	v_mov_b32_e32 v17, v26
	v_pk_mul_f32 v[22:23], v[16:17], v[98:99] op_sel_hi:[1,0]
	v_mov_b32_e32 v16, v8
	v_mov_b32_e32 v17, v24
	v_pk_mul_f32 v[38:39], v[16:17], v[98:99] op_sel_hi:[1,0]
	v_mov_b32_e32 v24, v9
	v_pk_mul_f32 v[104:105], v[38:39], v[38:39]
	v_pk_mul_f32 v[24:25], v[24:25], v[98:99] op_sel_hi:[1,0]
	v_mov_b32_e32 v26, v11
	v_add_f32_e32 v16, v104, v18
	v_pk_mul_f32 v[8:9], v[24:25], v[24:25]
	v_pk_mul_f32 v[94:95], v[22:23], v[22:23]
	v_pk_mul_f32 v[26:27], v[26:27], v[98:99] op_sel_hi:[1,0]
	v_add_f32_e32 v8, v8, v16
	v_mov_b32_e32 v16, v12
	v_mov_b32_e32 v17, v28
	v_pk_mul_f32 v[10:11], v[26:27], v[26:27]
	v_add_f32_e32 v8, v94, v8
	v_pk_mul_f32 v[16:17], v[16:17], v[98:99] op_sel_hi:[1,0]
	v_mov_b32_e32 v28, v13
	v_add_f32_e32 v8, v10, v8
	v_pk_mul_f32 v[106:107], v[16:17], v[16:17]
	v_pk_mul_f32 v[18:19], v[28:29], v[98:99] op_sel_hi:[1,0]
	v_add_f32_e32 v8, v106, v8
	v_pk_mul_f32 v[12:13], v[18:19], v[18:19]
	v_pk_mul_f32 v[30:31], v[30:31], v[98:99] op_sel_hi:[1,0]
	v_add_f32_e32 v8, v12, v8
	v_fmac_f32_e32 v8, v34, v34
	v_fmac_f32_e32 v8, v32, v32
	v_add_f32_e32 v8, v85, v8
	v_add_f32_e32 v8, v87, v8
	v_add_f32_e32 v8, v77, v8
	v_add_f32_e32 v8, v79, v8
	v_add_f32_e32 v8, v93, v8
	v_add_f32_e32 v8, v21, v8
	v_add_f32_e32 v8, v89, v8
	v_add_f32_e32 v8, v91, v8
	v_add_f32_e32 v8, v105, v8
	v_add_f32_e32 v8, v9, v8
	v_add_f32_e32 v8, v95, v8
	v_add_f32_e32 v8, v11, v8
	v_add_f32_e32 v8, v107, v8
	v_pk_mul_f32 v[62:63], v[30:31], v[30:31]
	v_add_f32_e32 v8, v13, v8
	v_add_f32_e32 v8, v62, v8
	v_add_f32_e32 v8, v63, v8
	v_mov_b32_e32 v9, v8
	s_nop 1
	v_permlane32_swap_b32_e32 v8, v9
	v_add_f32_e32 v8, v8, v9
	v_fmamk_f32 v8, v8, 0x3baaaaab, v227
	v_rsq_f32_e32 v8, v8
	v_mul_u32_u24_e32 v9, 0x190, v101
	v_lshlrev_b32_e32 v10, 3, v102
	v_add3_u32 v21, v46, v9, v10
	v_mul_f32_e32 v20, 0x3dd53b94, v8
	v_mul_f32_e32 v8, v97, v20
	v_mul_f32_e32 v9, v108, v20
	s_waitcnt vmcnt(0) lgkmcnt(0)
	v_mul_f32_e32 v8, v58, v8
	v_mul_f32_e32 v9, v59, v9
	v_mul_f32_e32 v10, v109, v20
	v_mul_f32_e32 v11, v110, v20
	v_mul_f32_e32 v10, v60, v10
	v_mul_f32_e32 v11, v61, v11
	v_cvt_pk_bf16_f32 v8, v8, v9
	v_cvt_pk_bf16_f32 v9, v10, v11
	ds_write_b64 v21, v[8:9]
	v_mul_f32_e32 v12, v111, v20
	v_mul_f32_e32 v13, v116, v20
	v_mul_f32_e32 v28, v117, v20
	v_mul_f32_e32 v29, v118, v20
	v_lshlrev_b32_e32 v184, 5, v102
	v_pk_mul_f32 v[14:15], v[14:15], v[20:21] op_sel_hi:[1,0]
	v_pk_mul_f32 v[40:41], v[40:41], v[20:21] op_sel_hi:[1,0]
	v_pk_mul_f32 v[6:7], v[6:7], v[20:21] op_sel_hi:[1,0]
	v_pk_mul_f32 v[4:5], v[4:5], v[20:21] op_sel_hi:[1,0]
	v_pk_mul_f32 v[0:1], v[0:1], v[20:21] op_sel_hi:[1,0]
	v_pk_mul_f32 v[2:3], v[2:3], v[20:21] op_sel_hi:[1,0]
	v_pk_mul_f32 v[38:39], v[38:39], v[20:21] op_sel_hi:[1,0]
	v_pk_mul_f32 v[24:25], v[24:25], v[20:21] op_sel_hi:[1,0]
	v_pk_mul_f32 v[22:23], v[22:23], v[20:21] op_sel_hi:[1,0]
	v_pk_mul_f32 v[26:27], v[26:27], v[20:21] op_sel_hi:[1,0]
	v_pk_mul_f32 v[16:17], v[16:17], v[20:21] op_sel_hi:[1,0]
	v_pk_mul_f32 v[18:19], v[18:19], v[20:21] op_sel_hi:[1,0]
	s_waitcnt vmcnt(0) lgkmcnt(0)
	v_mul_f32_e32 v8, v194, v12
	v_mul_f32_e32 v12, v112, v20
	v_mul_f32_e32 v9, v12, v195
	v_mul_f32_e32 v12, v113, v20
	v_mul_f32_e32 v10, v12, v196
	v_mul_f32_e32 v12, v114, v20
	v_mul_f32_e32 v11, v12, v197
	v_cvt_pk_bf16_f32 v8, v8, v9
	v_cvt_pk_bf16_f32 v9, v10, v11
	ds_write_b64 v21, v[8:9] offset:16
	v_mul_f32_e32 v12, v115, v20
	s_waitcnt vmcnt(0) lgkmcnt(0)
	v_mul_f32_e32 v8, v12, v198
	v_mul_f32_e32 v9, v13, v199
	v_mul_f32_e32 v10, v28, v200
	v_mul_f32_e32 v11, v29, v201
	v_cvt_pk_bf16_f32 v8, v8, v9
	v_cvt_pk_bf16_f32 v9, v10, v11
	ds_write_b64 v21, v[8:9] offset:32
	v_mul_f32_e32 v12, v119, v20
	v_mul_f32_e32 v13, v120, v20
	v_mul_f32_e32 v28, v121, v20
	v_mul_f32_e32 v29, v122, v20
	s_waitcnt vmcnt(0) lgkmcnt(0)
; DEV void epi_uq(f32x16 (&acc)[1][6], const Params& P, int layer, int batch, int m0, int head, int wid, int r32, int hi, char* lds) {
;     ...
; #pragma unroll
;   for (int ni = 0; ni < 4; ++ni)
; #pragma unroll
;     for (int r4 = 0; r4 < 4; ++r4) {
;       const int c = ni * 32 + r4 * 8 + hi * 4;
;       const float4 gg = *reinterpret_cast<const float4*>(g + c);
;       const f32x16& a = acc[0][ni];
;       st4lds(dst, c, a[r4 * 4] * inv * gg.x, a[r4 * 4 + 1] * inv * gg.y, a[r4 * 4 + 2] * inv * gg.z, a[r4 * 4 + 3] * inv * gg.w);
;     }
;   const int pos = batch ? t : (t & 4095);
;   const float2* rp = WS{P.ws}.rope() + (long)pos * 32;
; #pragma unroll
;   for (int r4 = 0; r4 < 4; ++r4) {
;     const int i = r4 * 8 + hi * 4;
;     const float4 g1 = *reinterpret_cast<const float4*>(g + 128 + i), g2 = *reinterpret_cast<const float4*>(g + 160 + i);
;     const float4 cs01 = *reinterpret_cast<const float4*>(rp + i), cs23 = *reinterpret_cast<const float4*>(rp + i + 2);
	v_mul_f32_e32 v8, v12, v202
	v_mul_f32_e32 v9, v13, v203
	v_mul_f32_e32 v10, v28, v204
	v_mul_f32_e32 v11, v29, v205
	v_cvt_pk_bf16_f32 v8, v8, v9
	v_cvt_pk_bf16_f32 v9, v10, v11
	ds_write_b64 v21, v[8:9] offset:48
	v_mul_f32_e32 v12, v123, v20
	v_mul_f32_e32 v13, v124, v20
	v_mul_f32_e32 v28, v125, v20
	v_mul_f32_e32 v29, v126, v20
	s_waitcnt vmcnt(0) lgkmcnt(0)
	v_mul_f32_e32 v8, v12, v206
	v_mul_f32_e32 v9, v13, v207
	v_mul_f32_e32 v10, v28, v208
	v_mul_f32_e32 v11, v29, v209
	v_cvt_pk_bf16_f32 v8, v8, v9
	v_cvt_pk_bf16_f32 v9, v10, v11
	ds_write_b64 v21, v[8:9] offset:64
	v_mul_f32_e32 v12, v127, v20
	v_mul_f32_e32 v13, v128, v20
	v_mul_f32_e32 v28, v129, v20
	v_mul_f32_e32 v29, v130, v20
	s_waitcnt vmcnt(0) lgkmcnt(0)
	v_mul_f32_e32 v8, v12, v210
	v_mul_f32_e32 v9, v13, v211
	v_mul_f32_e32 v10, v28, v212
	v_mul_f32_e32 v11, v29, v213
	v_cvt_pk_bf16_f32 v8, v8, v9
	v_cvt_pk_bf16_f32 v9, v10, v11
	ds_write_b64 v21, v[8:9] offset:80
	v_mul_f32_e32 v12, v80, v20
	v_mul_f32_e32 v13, v81, v20
	v_mul_f32_e32 v28, v82, v20
	v_mul_f32_e32 v29, v83, v20
	s_waitcnt vmcnt(0) lgkmcnt(0)
	v_mul_f32_e32 v8, v12, v214
	v_mul_f32_e32 v9, v13, v215
	v_mul_f32_e32 v10, v28, v216
	v_mul_f32_e32 v11, v29, v217
	v_cvt_pk_bf16_f32 v8, v8, v9
	v_cvt_pk_bf16_f32 v9, v10, v11
	ds_write_b64 v21, v[8:9] offset:96
	v_mul_f32_e32 v12, v72, v20
	v_mul_f32_e32 v13, v73, v20
	v_mul_f32_e32 v28, v74, v20
	v_mul_f32_e32 v29, v75, v20
	s_waitcnt vmcnt(0) lgkmcnt(0)
	v_mul_f32_e32 v8, v12, v218
	v_mul_f32_e32 v9, v13, v219
	v_mul_f32_e32 v10, v28, v220
	v_mul_f32_e32 v11, v29, v221
	v_cvt_pk_bf16_f32 v8, v8, v9
	v_cvt_pk_bf16_f32 v9, v10, v11
	ds_write_b64 v21, v[8:9] offset:112
	v_mul_f32_e32 v12, v68, v20
	v_mul_f32_e32 v13, v69, v20
	v_mul_f32_e32 v28, v70, v20
	v_mul_f32_e32 v29, v71, v20
	s_waitcnt vmcnt(0) lgkmcnt(0)
	v_mul_f32_e32 v8, v12, v222
	v_mul_f32_e32 v9, v13, v223
	v_mul_f32_e32 v10, v28, v224
	v_mul_f32_e32 v11, v29, v225
	v_cvt_pk_bf16_f32 v8, v8, v9
	v_cvt_pk_bf16_f32 v9, v10, v11
	ds_write_b64 v21, v[8:9] offset:128
	v_mul_f32_e32 v12, v64, v20
	v_mul_f32_e32 v13, v65, v20
	v_mul_f32_e32 v28, v66, v20
	v_mul_f32_e32 v29, v67, v20
	s_waitcnt vmcnt(0) lgkmcnt(0)
	v_mul_f32_e32 v8, v12, v232
	v_mul_f32_e32 v9, v13, v233
	v_mul_f32_e32 v10, v28, v234
	v_mul_f32_e32 v11, v29, v235
	v_cvt_pk_bf16_f32 v8, v8, v9
	v_cvt_pk_bf16_f32 v9, v10, v11
	ds_write_b64 v21, v[8:9] offset:144
	v_mul_f32_e32 v12, v54, v20
	v_mul_f32_e32 v13, v55, v20
	v_mul_f32_e32 v28, v56, v20
	v_mul_f32_e32 v29, v57, v20
	s_waitcnt vmcnt(0) lgkmcnt(0)
	v_mul_f32_e32 v8, v12, v236
	v_mul_f32_e32 v9, v13, v237
	v_mul_f32_e32 v10, v28, v238
	v_mul_f32_e32 v11, v29, v239
	v_cvt_pk_bf16_f32 v8, v8, v9
	v_cvt_pk_bf16_f32 v9, v10, v11
	ds_write_b64 v21, v[8:9] offset:160
	v_mul_f32_e32 v12, v50, v20
	v_mul_f32_e32 v13, v51, v20
	v_mul_f32_e32 v28, v52, v20
	v_mul_f32_e32 v29, v53, v20
	s_waitcnt vmcnt(0) lgkmcnt(0)
	v_mul_f32_e32 v8, v12, v240
	v_mul_f32_e32 v9, v13, v241
	v_mul_f32_e32 v10, v28, v242
	v_mul_f32_e32 v11, v29, v243
	v_cvt_pk_bf16_f32 v8, v8, v9
	v_cvt_pk_bf16_f32 v9, v10, v11
	ds_write_b64 v21, v[8:9] offset:176
	v_mul_f32_e32 v12, v48, v20
	v_mul_f32_e32 v13, v33, v20
	v_mul_f32_e32 v28, v49, v20
	v_mul_f32_e32 v29, v35, v20
	s_waitcnt vmcnt(0) lgkmcnt(0)
	v_mul_f32_e32 v8, v12, v244
	v_mul_f32_e32 v9, v13, v245
	v_mul_f32_e32 v10, v28, v246
	v_mul_f32_e32 v11, v29, v247
	v_cvt_pk_bf16_f32 v8, v8, v9
	v_cvt_pk_bf16_f32 v9, v10, v11
	ds_write_b64 v21, v[8:9] offset:192
	v_mul_f32_e32 v12, v131, v20
	v_mul_f32_e32 v13, v132, v20
	v_mul_f32_e32 v28, v133, v20
	v_mul_f32_e32 v29, v134, v20
	s_waitcnt vmcnt(0) lgkmcnt(0)
	v_mul_f32_e32 v8, v12, v248
	v_mul_f32_e32 v9, v13, v249
	v_mul_f32_e32 v10, v28, v250
	v_mul_f32_e32 v11, v29, v251
	v_cvt_pk_bf16_f32 v8, v8, v9
	v_cvt_pk_bf16_f32 v9, v10, v11
	ds_write_b64 v21, v[8:9] offset:208
	v_mul_f32_e32 v12, v135, v20
	v_mul_f32_e32 v13, v136, v20
	v_mul_f32_e32 v28, v137, v20
	v_mul_f32_e32 v29, v138, v20
	s_waitcnt vmcnt(0) lgkmcnt(0)
	v_mul_f32_e32 v8, v12, v170
	v_mul_f32_e32 v9, v13, v171
	v_mul_f32_e32 v10, v28, v172
	v_mul_f32_e32 v11, v29, v173
	v_cvt_pk_bf16_f32 v8, v8, v9
	v_cvt_pk_bf16_f32 v9, v10, v11
	ds_write_b64 v21, v[8:9] offset:224
	v_mul_f32_e32 v12, v139, v20
	v_mul_f32_e32 v13, v140, v20
	v_mul_f32_e32 v28, v141, v20
	v_mul_f32_e32 v29, v47, v20
	s_waitcnt vmcnt(0) lgkmcnt(0)
	v_mul_f32_e32 v8, v12, v174
	v_bitop3_b32 v12, v99, s3, v101 bitop3:0xc8
	v_cndmask_b32_e64 v12, v96, v12, s[26:27]
	v_mul_f32_e32 v9, v13, v175
	v_ashrrev_i32_e32 v13, 31, v12
	v_mul_f32_e32 v10, v28, v176
	v_mul_f32_e32 v11, v29, v177
	v_cvt_pk_bf16_f32 v8, v8, v9
	v_cvt_pk_bf16_f32 v9, v10, v11
	ds_write_b64 v21, v[8:9] offset:240
	v_lshlrev_b64 v[12:13], 8, v[12:13]
	flat_load_dwordx4 v[8:11], v[36:37] offset:1792
	flat_load_dwordx4 v[48:51], v[36:37] offset:1920
	v_lshl_add_u64 v[12:13], s[12:13], 0, v[12:13]
	v_lshl_add_u64 v[28:29], v[12:13], 0, v[184:185]
	flat_load_dwordx4 v[52:55], v[28:29]
	flat_load_dwordx4 v[56:59], v[28:29] offset:16
	v_pk_mul_f32 v[12:13], v[42:43], v[20:21] op_sel_hi:[1,0]
	v_pk_mul_f32 v[42:43], v[44:45], v[20:21] op_sel_hi:[1,0]
	s_waitcnt vmcnt(0) lgkmcnt(0)
; DEV void epi_uq(f32x16 (&acc)[1][6], const Params& P, int layer, int batch, int m0, int head, int wid, int r32, int hi, char* lds) {
;     ...
; #pragma unroll
;   for (int r4 = 0; r4 < 4; ++r4) {
;     const int i = r4 * 8 + hi * 4;
;     const float4 g1 = *reinterpret_cast<const float4*>(g + 128 + i), g2 = *reinterpret_cast<const float4*>(g + 160 + i);
;     const float4 cs01 = *reinterpret_cast<const float4*>(rp + i), cs23 = *reinterpret_cast<const float4*>(rp + i + 2);
;     const float x1[4] = {acc[0][4][r4 * 4] * inv * g1.x, acc[0][4][r4 * 4 + 1] * inv * g1.y, acc[0][4][r4 * 4 + 2] * inv * g1.z, acc[0][4][r4 * 4 + 3] * inv * g1.w};
;     const float x2[4] = {acc[0][5][r4 * 4] * inv * g2.x, acc[0][5][r4 * 4 + 1] * inv * g2.y, acc[0][5][r4 * 4 + 2] * inv * g2.z, acc[0][5][r4 * 4 + 3] * inv * g2.w};
;     const float cc[4] = {cs01.x, cs01.z, cs23.x, cs23.z}, sn[4] = {cs01.y, cs01.w, cs23.y, cs23.w};
;     st4lds(dst, 128 + i, x1[0] * cc[0] - x2[0] * sn[0], x1[1] * cc[1] - x2[1] * sn[1], x1[2] * cc[2] - x2[2] * sn[2], x1[3] * cc[3] - x2[3] * sn[3]);
;     st4lds(dst, 160 + i, x1[0] * sn[0] + x2[0] * cc[0], x1[1] * sn[1] + x2[1] * cc[1], x1[2] * sn[2] + x2[2] * cc[2], x1[3] * sn[3] + x2[3] * cc[3]);
;   }
	v_mov_b32_e32 v44, v8
	v_mov_b32_e32 v45, v48
	v_mov_b32_e32 v48, v9
	v_mov_b32_e32 v8, v10
	v_mov_b32_e32 v9, v50
	v_mov_b32_e32 v50, v11
	v_pk_mul_f32 v[10:11], v[12:13], v[44:45]
	v_pk_mul_f32 v[12:13], v[42:43], v[48:49]
	v_pk_mul_f32 v[8:9], v[14:15], v[8:9]
	v_pk_mul_f32 v[14:15], v[40:41], v[50:51]
	v_pk_mul_f32 v[40:41], v[10:11], v[52:53]
	v_pk_mul_f32 v[42:43], v[12:13], v[54:55]
	v_pk_mul_f32 v[44:45], v[8:9], v[56:57]
	v_pk_mul_f32 v[48:49], v[14:15], v[58:59]
	v_pk_mul_f32 v[10:11], v[10:11], v[52:53] op_sel:[1,0] op_sel_hi:[0,1]
	v_pk_mul_f32 v[12:13], v[12:13], v[54:55] op_sel:[1,0] op_sel_hi:[0,1]
	v_pk_mul_f32 v[8:9], v[8:9], v[56:57] op_sel:[1,0] op_sel_hi:[0,1]
	v_pk_mul_f32 v[14:15], v[14:15], v[58:59] op_sel:[1,0] op_sel_hi:[0,1]
	v_sub_f32_e32 v33, v40, v41
	v_sub_f32_e32 v35, v42, v43
	v_sub_f32_e32 v40, v44, v45
	v_sub_f32_e32 v41, v48, v49
	v_add_f32_e32 v10, v10, v11
	v_add_f32_e32 v11, v12, v13
	v_add_f32_e32 v12, v8, v9
	v_cvt_pk_bf16_f32 v8, v33, v35
	v_cvt_pk_bf16_f32 v9, v40, v41
	v_add_f32_e32 v13, v14, v15
	ds_write_b64 v21, v[8:9] offset:256
	v_cvt_pk_bf16_f32 v8, v10, v11
	v_cvt_pk_bf16_f32 v9, v12, v13
	ds_write_b64 v21, v[8:9] offset:320
	flat_load_dwordx4 v[8:11], v[36:37] offset:1824
	flat_load_dwordx4 v[12:15], v[36:37] offset:1952
	flat_load_dwordx4 v[40:43], v[28:29] offset:64
	flat_load_dwordx4 v[48:51], v[28:29] offset:80
	v_and_b32_e32 v33, 63, v100
	v_mul_lo_u16_e32 v35, 43, v33
	v_or_b32_e32 v47, 0xc0, v33
	v_or_b32_e32 v52, 0x1c0, v33
	v_or_b32_e32 v53, 0x280, v33
	v_or_b32_e32 v54, 0x240, v33
	v_or_b32_e32 v55, 0x2c0, v33
	v_lshrrev_b16_e32 v35, 10, v35
	v_mul_lo_u16_e32 v56, 0xab, v47
	v_mul_u32_u24_e32 v60, 0xaab, v52
	v_mul_u32_u24_e32 v62, 0xaab, v54
	v_mul_u32_u24_e32 v63, 0xaab, v53
	v_mul_u32_u24_e32 v64, 0xaab, v55
	v_lshrrev_b16_e32 v56, 12, v56
	v_mul_u32_u24_e32 v65, 0x190, v35
	v_lshrrev_b32_e32 v71, 16, v63
	s_waitcnt vmcnt(0) lgkmcnt(0)
	v_mov_b32_e32 v44, v8
	v_mov_b32_e32 v45, v12
	v_mov_b32_e32 v12, v9
	v_mov_b32_e32 v8, v10
	v_mov_b32_e32 v9, v14
	v_mov_b32_e32 v14, v11
	v_pk_mul_f32 v[6:7], v[6:7], v[44:45]
	v_pk_mul_f32 v[4:5], v[4:5], v[12:13]
	v_pk_mul_f32 v[0:1], v[0:1], v[8:9]
	v_pk_mul_f32 v[2:3], v[2:3], v[14:15]
	v_pk_mul_f32 v[8:9], v[6:7], v[40:41]
	v_pk_mul_f32 v[10:11], v[4:5], v[42:43]
	v_pk_mul_f32 v[12:13], v[0:1], v[48:49]
	v_pk_mul_f32 v[14:15], v[2:3], v[50:51]
	v_pk_mul_f32 v[4:5], v[4:5], v[42:43] op_sel:[1,0] op_sel_hi:[0,1]
	v_pk_mul_f32 v[0:1], v[0:1], v[48:49] op_sel:[1,0] op_sel_hi:[0,1]
	v_pk_mul_f32 v[6:7], v[6:7], v[40:41] op_sel:[1,0] op_sel_hi:[0,1]
	v_pk_mul_f32 v[2:3], v[2:3], v[50:51] op_sel:[1,0] op_sel_hi:[0,1]
	v_sub_f32_e32 v8, v8, v9
	v_sub_f32_e32 v9, v10, v11
	v_sub_f32_e32 v10, v12, v13
	v_sub_f32_e32 v11, v14, v15
	v_add_f32_e32 v4, v4, v5
	v_add_f32_e32 v5, v0, v1
	v_cvt_pk_bf16_f32 v0, v8, v9
	v_cvt_pk_bf16_f32 v1, v10, v11
	v_add_f32_e32 v6, v6, v7
	v_add_f32_e32 v2, v2, v3
	ds_write_b64 v21, v[0:1] offset:272
	v_cvt_pk_bf16_f32 v0, v6, v4
	v_cvt_pk_bf16_f32 v1, v5, v2
	ds_write_b64 v21, v[0:1] offset:336
	flat_load_dwordx4 v[12:15], v[36:37] offset:1856
	flat_load_dwordx4 v[8:11], v[36:37] offset:1984
	flat_load_dwordx4 v[0:3], v[28:29] offset:128
	flat_load_dwordx4 v[4:7], v[28:29] offset:144
	v_or_b32_e32 v44, 64, v33
	v_or_b32_e32 v45, 0x80, v33
	v_mul_lo_u16_e32 v42, 43, v44
	v_mul_lo_u16_e32 v43, 0xab, v45
	v_lshrrev_b16_e32 v66, 10, v42
	v_lshrrev_b16_e32 v67, 12, v43
	v_or_b32_e32 v48, 0x100, v33
	v_or_b32_e32 v49, 0x180, v33
	v_or_b32_e32 v50, 0x140, v33
	v_or_b32_e32 v51, 0x200, v33
	v_mul_u32_u24_e32 v57, 0xaab, v48
	v_mul_u32_u24_e32 v58, 0xaab, v50
	v_mul_u32_u24_e32 v59, 0xaab, v49
	v_mul_u32_u24_e32 v61, 0xaab, v51
	v_mad_i32_i24 v33, v35, s58, v33
	v_lshrrev_b32_e32 v57, 16, v57
	v_lshrrev_b32_e32 v68, 16, v58
	v_lshrrev_b32_e32 v69, 16, v59
	v_perm_b32 v58, v59, v58, s44
	v_lshrrev_b32_e32 v59, 16, v60
	v_lshrrev_b32_e32 v70, 16, v61
	v_perm_b32 v60, v61, v60, s44
	v_lshrrev_b32_e32 v61, 16, v62
	v_perm_b32 v62, v63, v62, s44
	v_lshrrev_b32_e32 v63, 16, v64
	v_lshlrev_b32_e32 v64, 4, v33
	v_mul_u32_u24_e32 v35, 0x300, v35
	v_lshlrev_b32_e32 v184, 1, v35
	v_mov_b32_e32 v35, v30
	v_mov_b64_e32 v[40:41], s[14:15]
	v_mad_i64_i32 v[40:41], s[2:3], v99, s39, v[40:41]
	v_lshl_add_u64 v[40:41], v[40:41], 0, s[22:23]
	v_mad_i32_i24 v55, v63, s58, v55
	v_lshlrev_b32_e32 v80, 4, v55
	s_waitcnt vmcnt(0) lgkmcnt(0)
; #define LDSP(T) __attribute__((address_space(3))) T*
; template <int NCH, int STRIDE> DEV void slab_flush(char* slab, u16* grow0, int gstride, int lane) {
;   asm volatile("s_waitcnt lgkmcnt(0)" ::: "memory");
; #pragma unroll
;   for (int i = 0; i < NCH / 2; ++i) {
;     const int q = i * 64 + lane, row = q / NCH, cc = q - row * NCH;
;     const u32x4 v = *(LDSP(const u32x4))(slab + row * STRIDE + cc * 16);
;     *reinterpret_cast<u32x4*>(grow0 + (long)row * gstride + cc * 8) = v;
;   }
;   asm volatile("s_waitcnt lgkmcnt(0)" ::: "memory");
; }
; DEV void epi_uq(f32x16 (&acc)[1][6], const Params& P, int layer, int batch, int m0, int head, int wid, int r32, int hi, char* lds) {
;     ...
;   for (int r4 = 0; r4 < 4; ++r4) {
;     const int i = r4 * 8 + hi * 4;
;     const float4 g1 = *reinterpret_cast<const float4*>(g + 128 + i), g2 = *reinterpret_cast<const float4*>(g + 160 + i);
;     const float4 cs01 = *reinterpret_cast<const float4*>(rp + i), cs23 = *reinterpret_cast<const float4*>(rp + i + 2);
;     const float x1[4] = {acc[0][4][r4 * 4] * inv * g1.x, acc[0][4][r4 * 4 + 1] * inv * g1.y, acc[0][4][r4 * 4 + 2] * inv * g1.z, acc[0][4][r4 * 4 + 3] * inv * g1.w};
;     const float x2[4] = {acc[0][5][r4 * 4] * inv * g2.x, acc[0][5][r4 * 4 + 1] * inv * g2.y, acc[0][5][r4 * 4 + 2] * inv * g2.z, acc[0][5][r4 * 4 + 3] * inv * g2.w};
;     const float cc[4] = {cs01.x, cs01.z, cs23.x, cs23.z}, sn[4] = {cs01.y, cs01.w, cs23.y, cs23.w};
;     st4lds(dst, 128 + i, x1[0] * cc[0] - x2[0] * sn[0], x1[1] * cc[1] - x2[1] * sn[1], x1[2] * cc[2] - x2[2] * sn[2], x1[3] * cc[3] - x2[3] * sn[3]);
;     st4lds(dst, 160 + i, x1[0] * sn[0] + x2[0] * cc[0], x1[1] * sn[1] + x2[1] * cc[1], x1[2] * sn[2] + x2[2] * cc[2], x1[3] * sn[3] + x2[3] * cc[3]);
;   }
;   slab_flush<24, 400>(slab, WS{P.ws}.QB() + (long)(m0 + wid * 32) * 768 + head * 192, 768, hi * 32 + r32);
	v_mov_b32_e32 v42, v12
	v_mov_b32_e32 v43, v8
	v_mov_b32_e32 v8, v13
	v_mov_b32_e32 v12, v14
	v_mov_b32_e32 v13, v10
	v_mov_b32_e32 v10, v15
	v_pk_mul_f32 v[14:15], v[38:39], v[42:43]
	v_pk_mul_f32 v[8:9], v[24:25], v[8:9]
	v_pk_mul_f32 v[12:13], v[22:23], v[12:13]
	v_pk_mul_f32 v[10:11], v[26:27], v[10:11]
	v_pk_mul_f32 v[22:23], v[14:15], v[0:1]
	v_pk_mul_f32 v[24:25], v[8:9], v[2:3]
	v_pk_mul_f32 v[26:27], v[12:13], v[4:5]
	v_pk_mul_f32 v[38:39], v[10:11], v[6:7]
	v_pk_mul_f32 v[0:1], v[14:15], v[0:1] op_sel:[1,0] op_sel_hi:[0,1]
	v_pk_mul_f32 v[2:3], v[8:9], v[2:3] op_sel:[1,0] op_sel_hi:[0,1]
	v_pk_mul_f32 v[4:5], v[12:13], v[4:5] op_sel:[1,0] op_sel_hi:[0,1]
	v_pk_mul_f32 v[6:7], v[10:11], v[6:7] op_sel:[1,0] op_sel_hi:[0,1]
	v_sub_f32_e32 v8, v22, v23
	v_sub_f32_e32 v9, v24, v25
	v_sub_f32_e32 v10, v26, v27
	v_sub_f32_e32 v11, v38, v39
	v_add_f32_e32 v12, v0, v1
	v_cvt_pk_bf16_f32 v0, v8, v9
	v_cvt_pk_bf16_f32 v1, v10, v11
	v_add_f32_e32 v2, v2, v3
	v_add_f32_e32 v3, v4, v5
	v_add_f32_e32 v4, v6, v7
	ds_write_b64 v21, v[0:1] offset:288
	v_cvt_pk_bf16_f32 v0, v12, v2
	v_cvt_pk_bf16_f32 v1, v3, v4
	ds_write_b64 v21, v[0:1] offset:352
	flat_load_dwordx4 v[0:3], v[36:37] offset:1888
	flat_load_dwordx4 v[4:7], v[36:37] offset:2016
	flat_load_dwordx4 v[8:11], v[28:29] offset:192
	flat_load_dwordx4 v[12:15], v[28:29] offset:208
	v_lshlrev_b32_e32 v22, 3, v33
	v_mad_i32_i24 v24, v66, s58, v44
	v_mad_i32_i24 v33, v56, s58, v47
	v_mad_i32_i24 v29, v57, s58, v48
	v_mul_u32_u24_e32 v25, 0x190, v66
	v_mad_i32_i24 v26, v67, s58, v45
	v_mul_u32_u24_e32 v27, 0x190, v67
	v_mul_u32_u24_e32 v45, 0x300, v67
	v_mul_u32_u24_e32 v39, 0x190, v57
	v_pk_mul_lo_u16 v42, v58, s37 op_sel_hi:[1,0]
	v_mad_i32_i24 v43, v69, s58, v49
	v_mad_i32_i24 v44, v59, s58, v52
	v_mad_i32_i24 v52, v71, s58, v53
	v_add3_u32 v53, v46, v65, v64
	v_lshlrev_b32_e32 v64, 4, v24
	v_lshlrev_b32_e32 v67, 4, v33
	v_lshlrev_b32_e32 v28, 3, v33
	v_lshlrev_b32_e32 v33, 4, v29
	v_mul_u32_u24_e32 v37, 0x190, v56
	v_mul_u32_u24_e32 v47, 0x300, v56
	v_mul_u32_u24_e32 v56, 0x300, v57
	v_mad_i32_i24 v38, v68, s58, v50
	v_mul_u32_u24_e32 v57, 0x300, v68
	v_pk_mul_lo_u16 v48, v60, s37 op_sel_hi:[1,0]
	v_mad_i32_i24 v49, v70, s58, v51
	v_mul_u32_u24_e32 v60, 0x300, v70
	v_mad_i32_i24 v50, v61, s58, v54
	v_mul_u32_u24_e32 v54, 0x300, v61
	v_mul_u32_u24_e32 v61, 0x300, v71
	v_and_b32_e32 v68, 0xfff0, v42
	v_lshrrev_b32_e32 v70, 16, v42
	v_lshlrev_b32_e32 v71, 4, v43
	v_lshlrev_b32_e32 v42, 3, v43
	v_add3_u32 v43, v46, v25, v64
	v_add3_u32 v64, v46, v39, v33
	v_mov_b32_e32 v33, v31
	v_pk_mul_f32 v[30:31], v[34:35], v[20:21] op_sel_hi:[1,0]
	v_pk_mul_f32 v[32:33], v[32:33], v[20:21] op_sel_hi:[1,0]
	v_ashrrev_i32_e32 v23, 31, v22
	v_mul_u32_u24_e32 v66, 0x300, v66
	v_lshlrev_b32_e32 v24, 3, v24
	v_ashrrev_i32_e32 v25, 31, v24
	v_lshlrev_b32_e32 v65, 4, v26
	v_and_b32_e32 v72, 0xfff0, v48
	v_lshrrev_b32_e32 v74, 16, v48
	v_lshlrev_b32_e32 v75, 4, v49
	v_lshlrev_b32_e32 v48, 3, v49
	v_add3_u32 v49, v46, v27, v65
	v_lshlrev_b32_e32 v26, 3, v26
	v_ashrrev_i32_e32 v27, 31, v26
	v_pk_mul_lo_u16 v51, v62, s37 op_sel_hi:[1,0]
	v_lshlrev_b32_e32 v36, 3, v29
	v_and_b32_e32 v76, 0xfff0, v51
	v_lshrrev_b32_e32 v78, 16, v51
	v_add3_u32 v51, v46, v37, v67
	v_ashrrev_i32_e32 v29, 31, v28
	v_ashrrev_i32_e32 v37, 31, v36
	v_mul_u32_u24_e32 v58, 0x300, v69
	v_lshlrev_b32_e32 v69, 4, v38
	v_add3_u32 v65, v46, v68, v69
	v_lshlrev_b32_e32 v38, 3, v38
	v_ashrrev_i32_e32 v39, 31, v38
	v_lshlrev_b32_e32 v73, 4, v44
	v_mul_u32_u24_e32 v59, 0x300, v59
	v_lshlrev_b32_e32 v44, 3, v44
	v_lshlrev_b32_e32 v77, 4, v50
	v_lshlrev_b32_e32 v50, 3, v50
	v_lshlrev_b32_e32 v79, 4, v52
	v_lshlrev_b32_e32 v52, 3, v52
	v_mul_u32_u24_e32 v62, 0x190, v63
	v_mul_u32_u24_e32 v63, 0x300, v63
	s_waitcnt vmcnt(0) lgkmcnt(0)
	v_mov_b32_e32 v34, v0
	v_mov_b32_e32 v35, v4
	v_mov_b32_e32 v4, v1
	v_mov_b32_e32 v0, v2
	v_mov_b32_e32 v1, v6
	v_mov_b32_e32 v6, v3
	v_pk_mul_f32 v[2:3], v[16:17], v[34:35]
	v_pk_mul_f32 v[4:5], v[18:19], v[4:5]
	v_pk_mul_f32 v[0:1], v[30:31], v[0:1]
	v_pk_mul_f32 v[6:7], v[32:33], v[6:7]
	v_pk_mul_f32 v[16:17], v[2:3], v[8:9]
	v_pk_mul_f32 v[18:19], v[4:5], v[10:11]
	v_pk_mul_f32 v[30:31], v[0:1], v[12:13]
	v_pk_mul_f32 v[32:33], v[6:7], v[14:15]
	v_pk_mul_f32 v[2:3], v[2:3], v[8:9] op_sel:[1,0] op_sel_hi:[0,1]
	v_pk_mul_f32 v[4:5], v[4:5], v[10:11] op_sel:[1,0] op_sel_hi:[0,1]
	v_pk_mul_f32 v[0:1], v[0:1], v[12:13] op_sel:[1,0] op_sel_hi:[0,1]
	v_pk_mul_f32 v[6:7], v[6:7], v[14:15] op_sel:[1,0] op_sel_hi:[0,1]
	v_sub_f32_e32 v8, v16, v17
	v_sub_f32_e32 v9, v18, v19
	v_sub_f32_e32 v10, v30, v31
	v_sub_f32_e32 v11, v32, v33
	v_add_f32_e32 v2, v2, v3
	v_add_f32_e32 v3, v4, v5
	v_add_f32_e32 v4, v0, v1
	v_cvt_pk_bf16_f32 v0, v8, v9
	v_cvt_pk_bf16_f32 v1, v10, v11
	v_add_f32_e32 v5, v6, v7
	ds_write_b64 v21, v[0:1] offset:304
	v_cvt_pk_bf16_f32 v0, v2, v3
	v_cvt_pk_bf16_f32 v1, v4, v5
	ds_write_b64 v21, v[0:1] offset:368
	s_waitcnt lgkmcnt(0)
	ds_read_b128 v[0:3], v53
	v_lshl_add_u64 v[4:5], v[40:41], 0, v[184:185]
	v_lshl_add_u64 v[4:5], v[22:23], 1, v[4:5]
	v_lshlrev_b32_e32 v184, 1, v66
	v_add3_u32 v6, v46, v70, v71
	s_waitcnt lgkmcnt(0)
	flat_store_dwordx4 v[4:5], v[0:3]
	ds_read_b128 v[0:3], v43
	v_lshl_add_u64 v[4:5], v[40:41], 0, v[184:185]
	v_lshl_add_u64 v[4:5], v[24:25], 1, v[4:5]
	v_lshlrev_b32_e32 v184, 1, v45
	v_ashrrev_i32_e32 v43, 31, v42
	s_waitcnt lgkmcnt(0)
	flat_store_dwordx4 v[4:5], v[0:3]
	ds_read_b128 v[0:3], v49
	v_lshl_add_u64 v[4:5], v[40:41], 0, v[184:185]
	v_lshl_add_u64 v[4:5], v[26:27], 1, v[4:5]
	v_lshlrev_b32_e32 v184, 1, v47
	v_add3_u32 v7, v46, v72, v73
	s_waitcnt lgkmcnt(0)
; #define LDSP(T) __attribute__((address_space(3))) T*
; #define GLOAD(kt, buf) do { _Pragma("unroll") for (int i = 0; i < 4; ++i) glds16(Ap + (long)i * 64 * lda + (kt) * 64, As + (buf) * 32768 + soff + i * 8192); \
;     _Pragma("unroll") for (int i = 0; i < NB; ++i) glds16(Bp + (long)i * 64 * ldb + (kt) * 64, Bs + (buf) * 32768 + soff + i * 8192); } while (0)
; template <int NCH, int STRIDE> DEV void slab_flush(char* slab, u16* grow0, int gstride, int lane) {
;   asm volatile("s_waitcnt lgkmcnt(0)" ::: "memory");
; #pragma unroll
;   for (int i = 0; i < NCH / 2; ++i) {
;     const int q = i * 64 + lane, row = q / NCH, cc = q - row * NCH;
;     const u32x4 v = *(LDSP(const u32x4))(slab + row * STRIDE + cc * 16);
;     *reinterpret_cast<u32x4*>(grow0 + (long)row * gstride + cc * 8) = v;
;   }
;   asm volatile("s_waitcnt lgkmcnt(0)" ::: "memory");
; }
; template <int WM, int WN, int BN, int EPI>
; DEV void gemm_tile(const u16* __restrict__ A, int lda, const u16* __restrict__ Bt, int ldb, int K, int m0, char* lds,
;                    const Params& P, int layer, int batch, int nt) {
;     ...
;   const int srow = tid >> 3, sch = (tid & 7) ^ ((srow >> 1) & 7);
;   const u16* Ap = A + (long)(m0 + srow) * lda + sch * 8;
;   const u16* Bp = Bt + (long)srow * ldb + sch * 8;
;   const int soff = tid * 16;
;     ...
;   GLOAD(0, 0); asm volatile("s_waitcnt vmcnt(0)" ::: "memory"); __syncthreads();
	flat_store_dwordx4 v[4:5], v[0:3]
	ds_read_b128 v[0:3], v51
	v_lshl_add_u64 v[4:5], v[40:41], 0, v[184:185]
	v_lshl_add_u64 v[4:5], v[28:29], 1, v[4:5]
	v_lshlrev_b32_e32 v184, 1, v56
	v_ashrrev_i32_e32 v45, 31, v44
	s_waitcnt lgkmcnt(0)
	flat_store_dwordx4 v[4:5], v[0:3]
	ds_read_b128 v[0:3], v64
	v_lshl_add_u64 v[4:5], v[40:41], 0, v[184:185]
	v_lshl_add_u64 v[4:5], v[36:37], 1, v[4:5]
	v_lshlrev_b32_e32 v184, 1, v57
	v_add3_u32 v8, v46, v74, v75
	s_waitcnt lgkmcnt(0)
	flat_store_dwordx4 v[4:5], v[0:3]
	ds_read_b128 v[0:3], v65
	v_lshl_add_u64 v[4:5], v[40:41], 0, v[184:185]
	v_lshl_add_u64 v[4:5], v[38:39], 1, v[4:5]
	v_lshlrev_b32_e32 v184, 1, v58
	v_ashrrev_i32_e32 v49, 31, v48
	s_waitcnt lgkmcnt(0)
	flat_store_dwordx4 v[4:5], v[0:3]
	ds_read_b128 v[0:3], v6
	v_lshl_add_u64 v[4:5], v[40:41], 0, v[184:185]
	v_lshl_add_u64 v[4:5], v[42:43], 1, v[4:5]
	v_lshlrev_b32_e32 v184, 1, v59
	v_add3_u32 v6, v46, v76, v77
	s_waitcnt lgkmcnt(0)
	flat_store_dwordx4 v[4:5], v[0:3]
	ds_read_b128 v[0:3], v7
	v_lshl_add_u64 v[4:5], v[40:41], 0, v[184:185]
	v_lshl_add_u64 v[4:5], v[44:45], 1, v[4:5]
	v_lshlrev_b32_e32 v184, 1, v60
	v_ashrrev_i32_e32 v51, 31, v50
	s_waitcnt lgkmcnt(0)
	flat_store_dwordx4 v[4:5], v[0:3]
	ds_read_b128 v[0:3], v8
	v_lshl_add_u64 v[4:5], v[40:41], 0, v[184:185]
	v_lshl_add_u64 v[4:5], v[48:49], 1, v[4:5]
	v_lshlrev_b32_e32 v184, 1, v54
	v_add3_u32 v7, v46, v78, v79
	s_waitcnt lgkmcnt(0)
	flat_store_dwordx4 v[4:5], v[0:3]
	ds_read_b128 v[0:3], v6
	v_lshl_add_u64 v[4:5], v[40:41], 0, v[184:185]
	v_lshl_add_u64 v[4:5], v[50:51], 1, v[4:5]
	v_lshlrev_b32_e32 v184, 1, v61
	v_ashrrev_i32_e32 v53, 31, v52
	s_waitcnt lgkmcnt(0)
	flat_store_dwordx4 v[4:5], v[0:3]
	ds_read_b128 v[0:3], v7
	v_lshl_add_u64 v[4:5], v[40:41], 0, v[184:185]
	v_lshl_add_u64 v[4:5], v[52:53], 1, v[4:5]
	v_add3_u32 v6, v46, v62, v80
	v_lshlrev_b32_e32 v184, 1, v63
	s_waitcnt lgkmcnt(0)
	flat_store_dwordx4 v[4:5], v[0:3]
	ds_read_b128 v[0:3], v6
	v_lshlrev_b32_e32 v6, 3, v55
	v_lshl_add_u64 v[4:5], v[40:41], 0, v[184:185]
	v_ashrrev_i32_e32 v7, 31, v6
	v_lshl_add_u64 v[4:5], v[6:7], 1, v[4:5]
	s_waitcnt lgkmcnt(0)
	flat_store_dwordx4 v[4:5], v[0:3]
	s_waitcnt lgkmcnt(0)
	s_waitcnt lgkmcnt(0)
	s_barrier
	s_cbranch_execnz .LBB0_355
.LBB0_359:
	s_lshl_b32 s2, s54, 16
	s_or_b32 s2, s2, s53
	s_add_u32 s60, s48, s2
	v_mov_b32_e32 v152, v226
	s_addc_u32 s61, s52, 0
	s_lshl_b32 s2, s55, 8
	s_mov_b64 s[62:63], 0xc000
	v_ashrrev_i32_e32 v0, 3, v152
	v_lshrrev_b32_e32 v1, 4, v152
	v_xor_b32_e32 v1, v1, v152
	v_add_u32_e32 v2, s2, v0
	v_ashrrev_i32_e32 v3, 31, v2
	v_lshlrev_b32_e32 v1, 4, v1
	v_lshlrev_b32_e32 v156, 4, v152
	v_lshlrev_b64 v[2:3], 8, v[2:3]
	v_and_b32_e32 v184, 0x70, v1
	v_ashrrev_i32_e32 v1, 31, v0
	v_add_u32_e32 v148, 0, v156
	v_lshl_add_u64 v[2:3], s[16:17], 0, v[2:3]
	v_lshlrev_b64 v[0:1], 8, v[0:1]
	v_readfirstlane_b32 s3, v148
	v_add_u32_e32 v5, 0x2000, v148
	v_lshl_add_u64 v[128:129], v[2:3], 0, v[184:185]
	v_lshl_add_u64 v[0:1], s[60:61], 0, v[0:1]
	s_mov_b32 m0, s3
	s_mov_b64 s[60:61], 0x4000
	v_readfirstlane_b32 s3, v5
	v_add_u32_e32 v5, 0x4000, v148
	global_load_lds_dwordx4 v[128:129], off
	v_lshl_add_u64 v[2:3], v[128:129], 0, s[60:61]
	s_mov_b32 m0, s3
	v_readfirstlane_b32 s3, v5
	v_add_u32_e32 v5, 0x6000, v148
	global_load_lds_dwordx4 v[2:3], off
	v_lshl_add_u64 v[2:3], v[128:129], 0, s[40:41]
	s_mov_b32 m0, s3
	v_readfirstlane_b32 s3, v5
	global_load_lds_dwordx4 v[2:3], off
	v_lshl_add_u64 v[2:3], v[128:129], 0, s[62:63]
	s_mov_b32 m0, s3
	s_add_i32 s3, 0, 0x10000
	global_load_lds_dwordx4 v[2:3], off
	v_add_u32_e32 v2, s3, v156
	v_add_u32_e32 v3, 0x2000, v2
	v_readfirstlane_b32 s22, v2
	v_lshl_add_u64 v[130:131], v[0:1], 0, v[184:185]
	s_mov_b32 m0, s22
	v_readfirstlane_b32 s22, v3
	v_add_u32_e32 v3, 0x4000, v2
	global_load_lds_dwordx4 v[130:131], off
	v_lshl_add_u64 v[0:1], v[130:131], 0, s[60:61]
	s_mov_b32 m0, s22
	v_readfirstlane_b32 s22, v3
	v_add_u32_e32 v2, 0x6000, v2
	global_load_lds_dwordx4 v[0:1], off
	v_lshl_add_u64 v[0:1], v[130:131], 0, s[40:41]
	s_mov_b32 m0, s22
	v_readfirstlane_b32 s22, v2
	v_and_b32_e32 v154, 31, v152
	global_load_lds_dwordx4 v[0:1], off
	v_lshl_add_u64 v[0:1], v[130:131], 0, s[62:63]
	s_mov_b32 m0, s22
	v_add_u32_e32 v5, 0x8000, v148
	global_load_lds_dwordx4 v[0:1], off
	v_lshlrev_b32_e32 v1, 7, v154
	v_add_u32_e32 v153, s3, v1
	s_add_i32 s3, 0, 0x18000
	v_ashrrev_i32_e32 v149, 6, v152
	v_add_u32_e32 v157, s3, v156
	v_readfirstlane_b32 s3, v5
	v_lshlrev_b32_e32 v0, 12, v149
	v_lshl_add_u64 v[2:3], v[128:129], 0, s[30:31]
	s_mov_b32 m0, s3
	v_readfirstlane_b32 s3, v157
	s_waitcnt vmcnt(0)
	s_waitcnt vmcnt(0) lgkmcnt(0)
	s_barrier
; #define SBAR() __builtin_amdgcn_sched_barrier(0)
; DEV void glds16(const u16* g, char* l) { __builtin_amdgcn_global_load_lds((const unsigned*)g, (unsigned*)l, 16, 0, 0); }
; template <int WM, int WN, int BN, int EPI>
; DEV void gemm_tile(const u16* __restrict__ A, int lda, const u16* __restrict__ Bt, int ldb, int K, int m0, char* lds,
;                    const Params& P, int layer, int batch, int nt) {
;     ...
;   for (int kt = 0; kt < nk; ++kt) {
;     const bool more = kt + 1 < nk;
;     const int nb = (kt + 1) & 1;
;     const char* as = As + (kt & 1) * 32768; const char* bs = Bs + (kt & 1) * 32768;
; #pragma unroll
;     for (int ks = 0; ks < 4; ++ks) {
;       if (more) { glds16(Ap + (long)ks * 64 * lda + (kt + 1) * 64, As + nb * 32768 + soff + ks * 8192);
;                   if (ks < NB) glds16(Bp + (long)ks * 64 * ldb + (kt + 1) * 64, Bs + nb * 32768 + soff + ks * 8192); }
;       SBAR();
;       bf16x8 xf[MI], wf[NI];
; #pragma unroll
;       for (int mi = 0; mi < MI; ++mi) xf[mi] = *reinterpret_cast<const bf16x8*>(as + swz128(wm * (MI * 32) + mi * 32 + r32, ks * 2 + hi));
; #pragma unroll
;       for (int ni = 0; ni < NI; ++ni) wf[ni] = *reinterpret_cast<const bf16x8*>(bs + swz128(wn * (NI * 32) + ni * 32 + r32, ks * 2 + hi));
; #pragma unroll
;       for (int mi = 0; mi < MI; ++mi)
; #pragma unroll
;         for (int ni = 0; ni < NI; ++ni) acc[mi][ni] = __builtin_amdgcn_mfma_f32_32x32x16_bf16(wf[ni], xf[mi], acc[mi][ni], 0, 0, 0);
;     }
	v_add3_u32 v151, 0, v0, v1
	v_lshl_add_u64 v[0:1], v[130:131], 0, s[30:31]
	global_load_lds_dwordx4 v[2:3], off
	s_mov_b32 m0, s3
	v_lshrrev_b32_e32 v4, 5, v152
	global_load_lds_dwordx4 v[0:1], off
	v_bfe_u32 v155, v152, 5, 1
	v_bfe_u32 v150, v152, 1, 3
	v_bitop3_b32 v0, v4, v150, 1 bitop3:0x6c
	v_lshlrev_b32_e32 v4, 4, v0
	v_add_u32_e32 v158, v153, v4
	ds_read_b128 v[0:3], v158
	v_add_u32_e32 v159, v151, v4
	ds_read_b128 v[64:67], v159
	v_add_u32_e32 v133, 0xa000, v148
	s_mov_b64 s[60:61], 0x4080
	v_add_u32_e32 v132, 0x2000, v157
	v_readfirstlane_b32 s3, v133
	v_lshl_add_u64 v[78:79], v[128:129], 0, s[60:61]
	s_mov_b32 m0, s3
	s_waitcnt lgkmcnt(0)
	v_mfma_f32_32x32x16_bf16 v[48:63], v[0:3], v[64:67], 0
	ds_read_b128 v[0:3], v158 offset:4096
	ds_read_b128 v[4:7], v158 offset:8192
	v_readfirstlane_b32 s3, v132
	v_lshl_add_u64 v[76:77], v[130:131], 0, s[60:61]
	s_waitcnt lgkmcnt(0)
	v_mfma_f32_32x32x16_bf16 v[32:47], v[0:3], v[64:67], 0
	ds_read_b128 v[0:3], v158 offset:12288
	ds_read_b128 v[68:71], v158 offset:16384
	s_waitcnt lgkmcnt(0)
	v_mfma_f32_32x32x16_bf16 v[112:127], v[68:71], v[64:67], 0
	ds_read_b128 v[68:71], v158 offset:20480
	ds_read_b128 v[72:75], v158 offset:24576
	s_waitcnt lgkmcnt(0)
	v_mfma_f32_32x32x16_bf16 v[96:111], v[68:71], v[64:67], 0
	ds_read_b128 v[68:71], v158 offset:28672
	global_load_lds_dwordx4 v[78:79], off
	s_mov_b32 m0, s3
	s_nop 0
	global_load_lds_dwordx4 v[76:77], off
	v_mfma_f32_32x32x16_bf16 v[16:31], v[4:7], v[64:67], 0
	v_mfma_f32_32x32x16_bf16 v[0:15], v[0:3], v[64:67], 0
	v_mfma_f32_32x32x16_bf16 v[80:95], v[72:75], v[64:67], 0
	s_waitcnt lgkmcnt(0)
	v_mfma_f32_32x32x16_bf16 v[64:79], v[68:71], v[64:67], 0
	v_bitop3_b32 v132, v155, v150, 2 bitop3:0x36
	v_lshlrev_b32_e32 v136, 4, v132
	v_add_u32_e32 v160, v153, v136
	ds_read_b128 v[132:135], v160
	v_add_u32_e32 v161, v151, v136
	ds_read_b128 v[136:139], v161
	v_add_u32_e32 v163, 0xc000, v148
	v_add_u32_e32 v162, 0x4000, v157
	v_readfirstlane_b32 s3, v163
	v_lshl_add_u64 v[146:147], v[128:129], 0, s[42:43]
	s_mov_b32 m0, s3
	v_readfirstlane_b32 s3, v162
	s_waitcnt lgkmcnt(0)
	v_mfma_f32_32x32x16_bf16 v[48:63], v[132:135], v[136:139], v[48:63]
	ds_read_b128 v[132:135], v160 offset:4096
	ds_read_b128 v[140:143], v160 offset:8192
	v_lshl_add_u64 v[144:145], v[130:131], 0, s[42:43]
	s_waitcnt lgkmcnt(0)
	v_mfma_f32_32x32x16_bf16 v[32:47], v[132:135], v[136:139], v[32:47]
	v_mfma_f32_32x32x16_bf16 v[16:31], v[140:143], v[136:139], v[16:31]
	ds_read_b128 v[132:135], v160 offset:12288
	ds_read_b128 v[140:143], v160 offset:16384
	s_waitcnt lgkmcnt(0)
	v_mfma_f32_32x32x16_bf16 v[0:15], v[132:135], v[136:139], v[0:15]
	v_mfma_f32_32x32x16_bf16 v[112:127], v[140:143], v[136:139], v[112:127]
	ds_read_b128 v[132:135], v160 offset:20480
	ds_read_b128 v[140:143], v160 offset:24576
	s_waitcnt lgkmcnt(0)
	v_mfma_f32_32x32x16_bf16 v[96:111], v[132:135], v[136:139], v[96:111]
	ds_read_b128 v[132:135], v160 offset:28672
	global_load_lds_dwordx4 v[146:147], off
	s_mov_b32 m0, s3
	s_nop 0
	global_load_lds_dwordx4 v[144:145], off
	v_mfma_f32_32x32x16_bf16 v[80:95], v[140:143], v[136:139], v[80:95]
	s_waitcnt lgkmcnt(0)
	v_mfma_f32_32x32x16_bf16 v[64:79], v[132:135], v[136:139], v[64:79]
	v_bitop3_b32 v132, v155, v150, 4 bitop3:0x36
	v_lshlrev_b32_e32 v136, 4, v132
	v_add_u32_e32 v144, v153, v136
	ds_read_b128 v[132:135], v144
	v_add_u32_e32 v145, v151, v136
	ds_read_b128 v[136:139], v145
	v_add_u32_e32 v147, 0xe000, v148
	s_mov_b64 s[60:61], 0xc080
	v_add_u32_e32 v146, 0x6000, v157
	v_readfirstlane_b32 s3, v147
	v_lshl_add_u64 v[128:129], v[128:129], 0, s[60:61]
	s_mov_b32 m0, s3
	s_waitcnt lgkmcnt(0)
	v_mfma_f32_32x32x16_bf16 v[48:63], v[132:135], v[136:139], v[48:63]
	ds_read_b128 v[132:135], v144 offset:4096
	ds_read_b128 v[140:143], v144 offset:8192
	v_readfirstlane_b32 s3, v146
	v_lshl_add_u64 v[130:131], v[130:131], 0, s[60:61]
	s_waitcnt lgkmcnt(0)
	v_mfma_f32_32x32x16_bf16 v[32:47], v[132:135], v[136:139], v[32:47]
	v_mfma_f32_32x32x16_bf16 v[16:31], v[140:143], v[136:139], v[16:31]
	ds_read_b128 v[132:135], v144 offset:12288
	ds_read_b128 v[140:143], v144 offset:16384
	s_waitcnt lgkmcnt(0)
	v_mfma_f32_32x32x16_bf16 v[0:15], v[132:135], v[136:139], v[0:15]
	v_mfma_f32_32x32x16_bf16 v[112:127], v[140:143], v[136:139], v[112:127]
	ds_read_b128 v[132:135], v144 offset:20480
	ds_read_b128 v[140:143], v144 offset:24576
	s_waitcnt lgkmcnt(0)
	v_mfma_f32_32x32x16_bf16 v[96:111], v[132:135], v[136:139], v[96:111]
	ds_read_b128 v[132:135], v144 offset:28672
	global_load_lds_dwordx4 v[128:129], off
	s_mov_b32 m0, s3
	s_nop 0
	global_load_lds_dwordx4 v[130:131], off
	v_mfma_f32_32x32x16_bf16 v[80:95], v[140:143], v[136:139], v[80:95]
	s_waitcnt lgkmcnt(0)
	v_mfma_f32_32x32x16_bf16 v[64:79], v[132:135], v[136:139], v[64:79]
	v_bitop3_b32 v128, v155, v150, 6 bitop3:0x36
	v_lshlrev_b32_e32 v132, 4, v128
	v_add_u32_e32 v148, v153, v132
	ds_read_b128 v[128:131], v148
	v_add_u32_e32 v140, v151, v132
	ds_read_b128 v[132:135], v140
	s_waitcnt lgkmcnt(0)
	v_mfma_f32_32x32x16_bf16 v[48:63], v[128:131], v[132:135], v[48:63]
	ds_read_b128 v[128:131], v148 offset:4096
	s_waitcnt lgkmcnt(0)
	v_mfma_f32_32x32x16_bf16 v[32:47], v[128:131], v[132:135], v[32:47]
	ds_read_b128 v[128:131], v148 offset:8192
	s_waitcnt lgkmcnt(0)
	v_mfma_f32_32x32x16_bf16 v[16:31], v[128:131], v[132:135], v[16:31]
	ds_read_b128 v[128:131], v148 offset:12288
	s_waitcnt lgkmcnt(0)
	v_mfma_f32_32x32x16_bf16 v[0:15], v[128:131], v[132:135], v[0:15]
	ds_read_b128 v[128:131], v148 offset:16384
	s_waitcnt lgkmcnt(0)
	v_mfma_f32_32x32x16_bf16 v[112:127], v[128:131], v[132:135], v[112:127]
	ds_read_b128 v[128:131], v148 offset:20480
	s_waitcnt lgkmcnt(0)
	v_mfma_f32_32x32x16_bf16 v[96:111], v[128:131], v[132:135], v[96:111]
	ds_read_b128 v[128:131], v148 offset:24576
	s_waitcnt lgkmcnt(0)
	v_mfma_f32_32x32x16_bf16 v[80:95], v[128:131], v[132:135], v[80:95]
	ds_read_b128 v[128:131], v148 offset:28672
	s_waitcnt vmcnt(0)
	s_waitcnt vmcnt(0) lgkmcnt(0)
	s_barrier
; #define SBAR() __builtin_amdgcn_sched_barrier(0)
;   DEV float* ssq_ckv() const { return (float*)(b + O_SSQCKV); }
; DEV void glds16(const u16* g, char* l) { __builtin_amdgcn_global_load_lds((const unsigned*)g, (unsigned*)l, 16, 0, 0); }
; DEV void epi_ukv(f32x16 (&acc)[1][8], const Params& P, int layer, int batch, int m0, int head, int wid, int r32, int hi, char* lds) {
;   const int t = m0 + wid * 32 + r32;
;   const float rc = __builtin_amdgcn_rsqf((WS{P.ws}.ssq_ckv()[t] + WS{P.ws}.ssq_ckv()[TB + t]) * (1.f / 128.f) + EPS);
; template <int WM, int WN, int BN, int EPI>
; DEV void gemm_tile(const u16* __restrict__ A, int lda, const u16* __restrict__ Bt, int ldb, int K, int m0, char* lds,
;                    const Params& P, int layer, int batch, int nt) {
;     ...
;   for (int kt = 0; kt < nk; ++kt) {
;     const bool more = kt + 1 < nk;
;     const int nb = (kt + 1) & 1;
;     const char* as = As + (kt & 1) * 32768; const char* bs = Bs + (kt & 1) * 32768;
; #pragma unroll
;     for (int ks = 0; ks < 4; ++ks) {
;       if (more) { glds16(Ap + (long)ks * 64 * lda + (kt + 1) * 64, As + nb * 32768 + soff + ks * 8192);
;                   if (ks < NB) glds16(Bp + (long)ks * 64 * ldb + (kt + 1) * 64, Bs + nb * 32768 + soff + ks * 8192); }
;       SBAR();
;       bf16x8 xf[MI], wf[NI];
; #pragma unroll
;       for (int mi = 0; mi < MI; ++mi) xf[mi] = *reinterpret_cast<const bf16x8*>(as + swz128(wm * (MI * 32) + mi * 32 + r32, ks * 2 + hi));
; #pragma unroll
;       for (int ni = 0; ni < NI; ++ni) wf[ni] = *reinterpret_cast<const bf16x8*>(bs + swz128(wn * (NI * 32) + ni * 32 + r32, ks * 2 + hi));
; #pragma unroll
;       for (int mi = 0; mi < MI; ++mi)
; #pragma unroll
;         for (int ni = 0; ni < NI; ++ni) acc[mi][ni] = __builtin_amdgcn_mfma_f32_32x32x16_bf16(wf[ni], xf[mi], acc[mi][ni], 0, 0, 0);
;     }
;     asm volatile("s_waitcnt vmcnt(0)" ::: "memory");
;     __syncthreads();
;   }
	v_mfma_f32_32x32x16_bf16 v[64:79], v[128:131], v[132:135], v[64:79]
	ds_read_b128 v[128:131], v158 offset:32768
	ds_read_b128 v[132:135], v159 offset:32768
	s_waitcnt lgkmcnt(0)
	v_mfma_f32_32x32x16_bf16 v[48:63], v[128:131], v[132:135], v[48:63]
	ds_read_b128 v[128:131], v158 offset:36864
	s_waitcnt lgkmcnt(0)
	v_mfma_f32_32x32x16_bf16 v[32:47], v[128:131], v[132:135], v[32:47]
	ds_read_b128 v[128:131], v158 offset:40960
	s_waitcnt lgkmcnt(0)
	v_mfma_f32_32x32x16_bf16 v[16:31], v[128:131], v[132:135], v[16:31]
	ds_read_b128 v[128:131], v158 offset:45056
	s_waitcnt lgkmcnt(0)
	v_mfma_f32_32x32x16_bf16 v[0:15], v[128:131], v[132:135], v[0:15]
	ds_read_b128 v[128:131], v158 offset:49152
	s_waitcnt lgkmcnt(0)
	v_mfma_f32_32x32x16_bf16 v[112:127], v[128:131], v[132:135], v[112:127]
	ds_read_b128 v[128:131], v158 offset:53248
	s_waitcnt lgkmcnt(0)
	v_mfma_f32_32x32x16_bf16 v[96:111], v[128:131], v[132:135], v[96:111]
	ds_read_b128 v[128:131], v158 offset:57344
	s_waitcnt lgkmcnt(0)
	v_mfma_f32_32x32x16_bf16 v[80:95], v[128:131], v[132:135], v[80:95]
	ds_read_b128 v[128:131], v158 offset:61440
	s_waitcnt lgkmcnt(0)
	v_mfma_f32_32x32x16_bf16 v[64:79], v[128:131], v[132:135], v[64:79]
	ds_read_b128 v[128:131], v160 offset:32768
	ds_read_b128 v[132:135], v161 offset:32768
	s_waitcnt lgkmcnt(0)
	v_mfma_f32_32x32x16_bf16 v[48:63], v[128:131], v[132:135], v[48:63]
	ds_read_b128 v[128:131], v160 offset:36864
	s_waitcnt lgkmcnt(0)
	v_mfma_f32_32x32x16_bf16 v[32:47], v[128:131], v[132:135], v[32:47]
	ds_read_b128 v[128:131], v160 offset:40960
	s_waitcnt lgkmcnt(0)
	v_mfma_f32_32x32x16_bf16 v[16:31], v[128:131], v[132:135], v[16:31]
	ds_read_b128 v[128:131], v160 offset:45056
	s_waitcnt lgkmcnt(0)
	v_mfma_f32_32x32x16_bf16 v[0:15], v[128:131], v[132:135], v[0:15]
	ds_read_b128 v[128:131], v160 offset:49152
	s_waitcnt lgkmcnt(0)
	v_mfma_f32_32x32x16_bf16 v[112:127], v[128:131], v[132:135], v[112:127]
	ds_read_b128 v[128:131], v160 offset:53248
	s_waitcnt lgkmcnt(0)
	v_mfma_f32_32x32x16_bf16 v[96:111], v[128:131], v[132:135], v[96:111]
	ds_read_b128 v[128:131], v160 offset:57344
	s_waitcnt lgkmcnt(0)
	v_mfma_f32_32x32x16_bf16 v[80:95], v[128:131], v[132:135], v[80:95]
	ds_read_b128 v[128:131], v160 offset:61440
	s_waitcnt lgkmcnt(0)
	v_mfma_f32_32x32x16_bf16 v[64:79], v[128:131], v[132:135], v[64:79]
	ds_read_b128 v[128:131], v144 offset:32768
	ds_read_b128 v[132:135], v145 offset:32768
	s_waitcnt lgkmcnt(0)
	v_mfma_f32_32x32x16_bf16 v[48:63], v[128:131], v[132:135], v[48:63]
	ds_read_b128 v[128:131], v144 offset:36864
	s_waitcnt lgkmcnt(0)
	v_mfma_f32_32x32x16_bf16 v[32:47], v[128:131], v[132:135], v[32:47]
	ds_read_b128 v[128:131], v144 offset:40960
	s_waitcnt lgkmcnt(0)
	v_mfma_f32_32x32x16_bf16 v[16:31], v[128:131], v[132:135], v[16:31]
	ds_read_b128 v[128:131], v144 offset:45056
	s_waitcnt lgkmcnt(0)
	v_mfma_f32_32x32x16_bf16 v[0:15], v[128:131], v[132:135], v[0:15]
	ds_read_b128 v[128:131], v144 offset:49152
	s_waitcnt lgkmcnt(0)
	v_mfma_f32_32x32x16_bf16 v[112:127], v[128:131], v[132:135], v[112:127]
	ds_read_b128 v[128:131], v144 offset:53248
	s_waitcnt lgkmcnt(0)
	v_mfma_f32_32x32x16_bf16 v[96:111], v[128:131], v[132:135], v[96:111]
	ds_read_b128 v[128:131], v144 offset:57344
	s_waitcnt lgkmcnt(0)
	v_mfma_f32_32x32x16_bf16 v[80:95], v[128:131], v[132:135], v[80:95]
	ds_read_b128 v[128:131], v144 offset:61440
	s_waitcnt lgkmcnt(0)
	v_mfma_f32_32x32x16_bf16 v[64:79], v[128:131], v[132:135], v[64:79]
	ds_read_b128 v[136:139], v148 offset:49152
	ds_read_b128 v[128:131], v140 offset:32768
	ds_read_b128 v[132:135], v148 offset:45056
	ds_read_b128 v[140:143], v148 offset:32768
	ds_read_b128 v[158:161], v148 offset:53248
	v_lshlrev_b32_e32 v157, 3, v155
	s_waitcnt lgkmcnt(3)
	v_mfma_f32_32x32x16_bf16 v[112:127], v[136:139], v[128:131], v[112:127]
	ds_read_b128 v[144:147], v148 offset:36864
	ds_read_b128 v[136:139], v148 offset:40960
	ds_read_b128 v[162:165], v148 offset:57344
	ds_read_b128 v[166:169], v148 offset:61440
	v_lshl_add_u32 v148, v149, 5, s2
	v_or_b32_e32 v150, v148, v154
	v_ashrrev_i32_e32 v151, 31, v150
	s_waitcnt vmcnt(0)
	s_waitcnt lgkmcnt(0)
	s_barrier
	v_mfma_f32_32x32x16_bf16 v[96:111], v[158:161], v[128:131], v[96:111]
	v_lshl_add_u64 v[158:159], v[150:151], 2, s[18:19]
	v_add_co_u32_e32 v160, vcc, s93, v158
	s_nop 1
	v_addc_co_u32_e32 v161, vcc, 0, v159, vcc
	flat_load_dword v153, v[158:159]
	s_nop 0
	flat_load_dword v158, v[160:161]
	v_mfma_f32_32x32x16_bf16 v[80:95], v[162:165], v[128:131], v[80:95]
	v_mul_lo_u32 v149, v149, s99
	v_mul_u32_u24_e32 v159, 0x110, v154
	v_and_b32_e32 v184, 0xf0, v156
	s_lshl_b32 s22, s54, 8
	s_movk_i32 s2, 0xfff
	s_waitcnt vmcnt(0) lgkmcnt(0)
;   DEV u16* VB() const { return (u16*)(b + O_VB); }
;   DEV float* ssq_ckv() const { return (float*)(b + O_SSQCKV); }
; DEV void epi_ukv(f32x16 (&acc)[1][8], const Params& P, int layer, int batch, int m0, int head, int wid, int r32, int hi, char* lds) {
;   const int t = m0 + wid * 32 + r32;
;   const float rc = __builtin_amdgcn_rsqf((WS{P.ws}.ssq_ckv()[t] + WS{P.ws}.ssq_ckv()[TB + t]) * (1.f / 128.f) + EPS);
;   char* slab = lds + wid * 12800; char* vdst = slab + r32 * 272;
; #pragma unroll
;   for (int ni = 4; ni < 8; ++ni)
; #pragma unroll
;     for (int r4 = 0; r4 < 4; ++r4) {
;       const f32x16& a = acc[0][ni];
;       st4lds(vdst, (ni - 4) * 32 + r4 * 8 + hi * 4, a[r4 * 4] * rc, a[r4 * 4 + 1] * rc, a[r4 * 4 + 2] * rc, a[r4 * 4 + 3] * rc);
;     }
;   slab_flush<16, 272>(slab, WS{P.ws}.VB() + (long)(m0 + wid * 32) * 512 + head * 128, 512, hi * 32 + r32);
	v_add_f32_e32 v153, v153, v158
	v_fmamk_f32 v153, v153, 0x3c000000, v227
	v_rsq_f32_e32 v158, v153
	v_add_u32_e32 v153, 0, v149
	v_add3_u32 v149, v153, v159, v157
	v_mfma_f32_32x32x16_bf16 v[64:79], v[166:169], v[128:131], v[64:79]
	v_mul_f32_e32 v112, v112, v158
	v_mul_f32_e32 v113, v113, v158
	v_mul_f32_e32 v114, v114, v158
	v_mul_f32_e32 v115, v115, v158
	v_mul_f32_e32 v159, v80, v158
	v_mul_f32_e32 v160, v81, v158
	v_cvt_pk_bf16_f32 v80, v112, v113
	v_cvt_pk_bf16_f32 v81, v114, v115
	v_mul_f32_e32 v116, v116, v158
	v_mul_f32_e32 v117, v117, v158
	v_mul_f32_e32 v118, v118, v158
	v_mul_f32_e32 v119, v119, v158
	ds_write_b64 v149, v[80:81]
	v_cvt_pk_bf16_f32 v80, v116, v117
	v_cvt_pk_bf16_f32 v81, v118, v119
	v_mul_f32_e32 v120, v120, v158
	v_mul_f32_e32 v121, v121, v158
	v_mul_f32_e32 v122, v122, v158
	v_mul_f32_e32 v123, v123, v158
	ds_write_b64 v149, v[80:81] offset:16
	v_cvt_pk_bf16_f32 v80, v120, v121
	v_cvt_pk_bf16_f32 v81, v122, v123
	v_mul_f32_e32 v124, v124, v158
	v_mul_f32_e32 v125, v125, v158
	v_mul_f32_e32 v126, v126, v158
	v_mul_f32_e32 v127, v127, v158
	ds_write_b64 v149, v[80:81] offset:32
	v_cvt_pk_bf16_f32 v80, v124, v125
	v_cvt_pk_bf16_f32 v81, v126, v127
	v_mul_f32_e32 v96, v96, v158
	v_mul_f32_e32 v97, v97, v158
	v_mul_f32_e32 v98, v98, v158
	v_mul_f32_e32 v99, v99, v158
	ds_write_b64 v149, v[80:81] offset:48
	v_cvt_pk_bf16_f32 v80, v96, v97
	v_cvt_pk_bf16_f32 v81, v98, v99
	v_mul_f32_e32 v100, v100, v158
	v_mul_f32_e32 v101, v101, v158
	v_mul_f32_e32 v102, v102, v158
	v_mul_f32_e32 v103, v103, v158
	ds_write_b64 v149, v[80:81] offset:64
	v_cvt_pk_bf16_f32 v80, v100, v101
	v_cvt_pk_bf16_f32 v81, v102, v103
	v_mul_f32_e32 v104, v104, v158
	v_mul_f32_e32 v105, v105, v158
	v_mul_f32_e32 v106, v106, v158
	v_mul_f32_e32 v107, v107, v158
	ds_write_b64 v149, v[80:81] offset:80
	v_cvt_pk_bf16_f32 v80, v104, v105
	v_cvt_pk_bf16_f32 v81, v106, v107
	v_mul_f32_e32 v108, v108, v158
	v_mul_f32_e32 v109, v109, v158
	v_mul_f32_e32 v110, v110, v158
	v_mul_f32_e32 v111, v111, v158
	ds_write_b64 v149, v[80:81] offset:96
	v_cvt_pk_bf16_f32 v80, v108, v109
	v_cvt_pk_bf16_f32 v81, v110, v111
	v_mul_f32_e32 v82, v82, v158
	v_mul_f32_e32 v83, v83, v158
	ds_write_b64 v149, v[80:81] offset:112
	v_cvt_pk_bf16_f32 v80, v159, v160
	v_cvt_pk_bf16_f32 v81, v82, v83
	v_mul_f32_e32 v84, v84, v158
	v_mul_f32_e32 v85, v85, v158
	v_mul_f32_e32 v86, v86, v158
	v_mul_f32_e32 v87, v87, v158
	ds_write_b64 v149, v[80:81] offset:128
	v_cvt_pk_bf16_f32 v80, v84, v85
	v_cvt_pk_bf16_f32 v81, v86, v87
	ds_write_b64 v149, v[80:81] offset:144
	v_mul_f32_e32 v80, v88, v158
	v_mul_f32_e32 v81, v89, v158
	v_mul_f32_e32 v82, v90, v158
	v_mul_f32_e32 v83, v91, v158
	v_cvt_pk_bf16_f32 v80, v80, v81
	v_cvt_pk_bf16_f32 v81, v82, v83
	ds_write_b64 v149, v[80:81] offset:160
	v_mul_f32_e32 v80, v92, v158
	v_mul_f32_e32 v81, v93, v158
	v_mul_f32_e32 v64, v64, v158
	v_mul_f32_e32 v65, v65, v158
	v_mul_f32_e32 v82, v94, v158
	v_mul_f32_e32 v83, v95, v158
	v_cvt_pk_bf16_f32 v80, v80, v81
	v_cvt_pk_bf16_f32 v81, v82, v83
	ds_write_b64 v149, v[80:81] offset:176
	v_mul_f32_e32 v66, v66, v158
	v_mul_f32_e32 v67, v67, v158
	v_cvt_pk_bf16_f32 v64, v64, v65
	v_cvt_pk_bf16_f32 v65, v66, v67
	ds_write_b64 v149, v[64:65] offset:192
	v_mul_f32_e32 v64, v68, v158
	v_mul_f32_e32 v65, v69, v158
	v_mul_f32_e32 v66, v70, v158
	v_mul_f32_e32 v67, v71, v158
	v_cvt_pk_bf16_f32 v64, v64, v65
	v_cvt_pk_bf16_f32 v65, v66, v67
	ds_write_b64 v149, v[64:65] offset:208
	v_mul_f32_e32 v64, v72, v158
	v_mul_f32_e32 v65, v73, v158
	v_mul_f32_e32 v66, v74, v158
	v_mul_f32_e32 v67, v75, v158
	v_cvt_pk_bf16_f32 v64, v64, v65
	v_cvt_pk_bf16_f32 v65, v66, v67
	ds_write_b64 v149, v[64:65] offset:224
	v_mul_f32_e32 v64, v76, v158
	v_mul_f32_e32 v65, v77, v158
	v_mul_f32_e32 v66, v78, v158
	v_mul_f32_e32 v67, v79, v158
	v_cvt_pk_bf16_f32 v64, v64, v65
	v_cvt_pk_bf16_f32 v65, v66, v67
	ds_write_b64 v149, v[64:65] offset:240
	v_ashrrev_i32_e32 v149, 31, v148
	v_lshlrev_b64 v[64:65], 10, v[148:149]
	v_bfe_u32 v70, v152, 4, 2
	v_lshl_add_u64 v[68:69], s[24:25], 0, v[64:65]
	v_mul_u32_u24_e32 v64, 0x110, v70
	s_waitcnt lgkmcnt(0)
	v_add3_u32 v72, v153, v184, v64
	ds_read_b128 v[64:67], v72
	v_lshl_add_u64 v[68:69], v[68:69], 0, s[22:23]
	v_lshl_add_u64 v[68:69], v[68:69], 0, v[184:185]
	v_lshlrev_b32_e32 v184, 10, v70
	v_lshl_add_u64 v[70:71], v[68:69], 0, v[184:185]
	s_waitcnt lgkmcnt(0)
	flat_store_dwordx4 v[70:71], v[64:67]
	ds_read_b128 v[64:67], v72 offset:1088
	v_or_b32_e32 v70, 0x1000, v184
	v_mov_b32_e32 v71, v185
	v_lshl_add_u64 v[70:71], v[68:69], 0, v[70:71]
	v_mfma_f32_32x32x16_bf16 v[32:47], v[144:147], v[128:131], v[32:47]
	s_waitcnt lgkmcnt(0)
	flat_store_dwordx4 v[70:71], v[64:67]
	ds_read_b128 v[64:67], v72 offset:2176
	v_or_b32_e32 v70, 0x2000, v184
	v_mov_b32_e32 v71, v185
	v_lshl_add_u64 v[70:71], v[68:69], 0, v[70:71]
	s_mul_i32 s22, s54, 0x180
	s_waitcnt lgkmcnt(0)
	flat_store_dwordx4 v[70:71], v[64:67]
	ds_read_b128 v[64:67], v72 offset:3264
	v_or_b32_e32 v70, 0x3000, v184
	v_mov_b32_e32 v71, v185
	v_lshl_add_u64 v[70:71], v[68:69], 0, v[70:71]
	v_mfma_f32_32x32x16_bf16 v[48:63], v[140:143], v[128:131], v[48:63]
	s_waitcnt lgkmcnt(0)
	flat_store_dwordx4 v[70:71], v[64:67]
	ds_read_b128 v[64:67], v72 offset:4352
	v_or_b32_e32 v70, 0x4000, v184
	v_mov_b32_e32 v71, v185
	v_lshl_add_u64 v[70:71], v[68:69], 0, v[70:71]
	v_mul_f32_e32 v75, v32, v158
	s_waitcnt lgkmcnt(0)
	flat_store_dwordx4 v[70:71], v[64:67]
	ds_read_b128 v[64:67], v72 offset:5440
	v_or_b32_e32 v70, 0x5000, v184
	v_mov_b32_e32 v71, v185
	v_lshl_add_u64 v[70:71], v[68:69], 0, v[70:71]
	v_mul_f32_e32 v76, v33, v158
	s_waitcnt lgkmcnt(0)
;   DEV u16* VB() const { return (u16*)(b + O_VB); }
; DEV void epi_ukv(f32x16 (&acc)[1][8], const Params& P, int layer, int batch, int m0, int head, int wid, int r32, int hi, char* lds) {
;     ...
;   slab_flush<16, 272>(slab, WS{P.ws}.VB() + (long)(m0 + wid * 32) * 512 + head * 128, 512, hi * 32 + r32);
;   float s = 0.f;
; #pragma unroll
;   for (int ni = 0; ni < 4; ++ni)
; #pragma unroll
;     for (int r = 0; r < 16; ++r) { acc[0][ni][r] *= rc; s += acc[0][ni][r] * acc[0][ni][r]; }
;   float4 kr[2][4];
; #pragma unroll
;   for (int b = 0; b < 2; ++b)
; #pragma unroll
;     for (int r4 = 0; r4 < 4; ++r4) {
;       kr[b][r4] = *reinterpret_cast<const float4*>(WS{P.ws}.KR() + (long)t * 64 + b * 32 + r4 * 8 + hi * 4);
;       s += kr[b][r4].x * kr[b][r4].x + kr[b][r4].y * kr[b][r4].y + kr[b][r4].z * kr[b][r4].z + kr[b][r4].w * kr[b][r4].w;
;     }
;     ...
;   const float* g = WS{P.ws}.consts() + layer * 1024 + 512;
;   char* dst = slab + r32 * 400;
; #pragma unroll
;   for (int ni = 0; ni < 4; ++ni)
; #pragma unroll
;     for (int r4 = 0; r4 < 4; ++r4) {
;       const int c = ni * 32 + r4 * 8 + hi * 4;
;       const float4 gg = *reinterpret_cast<const float4*>(g + c);
	flat_store_dwordx4 v[70:71], v[64:67]
	ds_read_b128 v[64:67], v72 offset:6528
	v_or_b32_e32 v70, 0x6000, v184
	v_mov_b32_e32 v71, v185
	v_lshl_add_u64 v[70:71], v[68:69], 0, v[70:71]
	v_or_b32_e32 v184, 0x7000, v184
	s_waitcnt lgkmcnt(0)
	flat_store_dwordx4 v[70:71], v[64:67]
	ds_read_b128 v[64:67], v72 offset:7616
	v_lshl_add_u64 v[68:69], v[68:69], 0, v[184:185]
	v_lshlrev_b64 v[32:33], 8, v[150:151]
	v_lshl_add_u64 v[32:33], s[68:69], 0, v[32:33]
	v_lshlrev_b32_e32 v184, 4, v155
	s_waitcnt lgkmcnt(0)
	flat_store_dwordx4 v[68:69], v[64:67]
	s_waitcnt lgkmcnt(0)
	v_mul_f32_e32 v73, v56, v158
	v_mul_f32_e32 v74, v57, v158
	v_lshl_add_u64 v[56:57], v[32:33], 0, v[184:185]
	v_mul_f32_e32 v64, v48, v158
	v_mul_f32_e32 v65, v49, v158
	v_mul_f32_e32 v67, v50, v158
	v_mul_f32_e32 v68, v51, v158
	flat_load_dwordx4 v[48:51], v[56:57]
	v_mul_f32_e32 v83, v40, v158
	v_mul_f32_e32 v84, v41, v158
	v_mul_f32_e32 v85, v42, v158
	v_mul_f32_e32 v86, v43, v158
	flat_load_dwordx4 v[40:43], v[56:57] offset:32
	v_mul_f32_e32 v79, v36, v158
	v_mul_f32_e32 v80, v37, v158
	v_mul_f32_e32 v81, v38, v158
	v_mul_f32_e32 v82, v39, v158
	flat_load_dwordx4 v[36:39], v[56:57] offset:64
	v_mfma_f32_32x32x16_bf16 v[16:31], v[136:139], v[128:131], v[16:31]
	v_mul_f32_e32 v77, v34, v158
	v_mul_f32_e32 v78, v35, v158
	flat_load_dwordx4 v[32:35], v[56:57] offset:96
	v_mul_f32_e32 v69, v52, v158
	v_mul_f32_e32 v70, v53, v158
	v_mul_f32_e32 v71, v54, v158
	v_mul_f32_e32 v72, v55, v158
	v_mul_f32_e32 v87, v44, v158
	v_mul_f32_e32 v88, v45, v158
	v_mul_f32_e32 v89, v46, v158
	v_mul_f32_e32 v90, v47, v158
	flat_load_dwordx4 v[52:55], v[56:57] offset:128
	flat_load_dwordx4 v[44:47], v[56:57] offset:160
	v_mul_f32_e32 v91, v16, v158
	v_mul_f32_e32 v92, v17, v158
	v_mul_f32_e32 v93, v18, v158
	v_mul_f32_e32 v94, v19, v158
	v_mul_f32_e32 v95, v20, v158
	v_mul_f32_e32 v96, v21, v158
	v_mul_f32_e32 v97, v22, v158
	v_mul_f32_e32 v98, v23, v158
	flat_load_dwordx4 v[20:23], v[56:57] offset:192
	flat_load_dwordx4 v[16:19], v[56:57] offset:224
	v_mul_f32_e32 v66, v65, v65
	v_fmac_f32_e32 v66, v64, v64
	v_fmac_f32_e32 v66, v67, v67
	v_fmac_f32_e32 v66, v68, v68
	v_fmac_f32_e32 v66, v69, v69
	v_mfma_f32_32x32x16_bf16 v[0:15], v[132:135], v[128:131], v[0:15]
	v_fmac_f32_e32 v66, v70, v70
	v_fmac_f32_e32 v66, v71, v71
	v_fmac_f32_e32 v66, v72, v72
	v_fmac_f32_e32 v66, v73, v73
	v_fmac_f32_e32 v66, v74, v74
	v_mul_f32_e32 v58, v58, v158
	v_fmac_f32_e32 v66, v58, v58
	v_mul_f32_e32 v59, v59, v158
	v_fmac_f32_e32 v66, v59, v59
	v_mul_f32_e32 v60, v60, v158
	v_fmac_f32_e32 v66, v60, v60
	v_mul_f32_e32 v61, v61, v158
	v_mul_f32_e32 v101, v26, v158
	v_mul_f32_e32 v56, v27, v158
	v_lshl_add_u64 v[26:27], s[10:11], 0, v[184:185]
	v_fmac_f32_e32 v66, v61, v61
	v_mul_f32_e32 v62, v62, v158
	v_mul_f32_e32 v57, v0, v158
	v_mul_f32_e32 v102, v1, v158
	v_mul_f32_e32 v103, v2, v158
	v_mul_f32_e32 v104, v3, v158
	flat_load_dwordx4 v[0:3], v[26:27] offset:2048
	global_load_dwordx4 v[194:197], v[26:27], off offset:2080
	global_load_dwordx4 v[198:201], v[26:27], off offset:2112
	global_load_dwordx4 v[202:205], v[26:27], off offset:2144
	global_load_dwordx4 v[206:209], v[26:27], off offset:2176
	global_load_dwordx4 v[210:213], v[26:27], off offset:2208
	global_load_dwordx4 v[214:217], v[26:27], off offset:2240
	global_load_dwordx4 v[218:221], v[26:27], off offset:2272
	global_load_dwordx4 v[222:225], v[26:27], off offset:2304
	global_load_dwordx4 v[232:235], v[26:27], off offset:2336
	global_load_dwordx4 v[236:239], v[26:27], off offset:2368
	global_load_dwordx4 v[240:243], v[26:27], off offset:2400
	global_load_dwordx4 v[244:247], v[26:27], off offset:2432
	global_load_dwordx4 v[248:251], v[26:27], off offset:2464
	global_load_dwordx4 v[170:173], v[26:27], off offset:2496
	global_load_dwordx4 v[174:177], v[26:27], off offset:2528
	v_fmac_f32_e32 v66, v62, v62
	v_mul_f32_e32 v63, v63, v158
	v_fmac_f32_e32 v66, v63, v63
	v_fmac_f32_e32 v66, v75, v75
	v_fmac_f32_e32 v66, v76, v76
	v_fmac_f32_e32 v66, v77, v77
	v_fmac_f32_e32 v66, v78, v78
	v_fmac_f32_e32 v66, v79, v79
	v_fmac_f32_e32 v66, v80, v80
	v_fmac_f32_e32 v66, v81, v81
	v_fmac_f32_e32 v66, v82, v82
	v_fmac_f32_e32 v66, v83, v83
	v_fmac_f32_e32 v66, v84, v84
	v_fmac_f32_e32 v66, v85, v85
	v_fmac_f32_e32 v66, v86, v86
	v_fmac_f32_e32 v66, v87, v87
	v_fmac_f32_e32 v66, v88, v88
	v_fmac_f32_e32 v66, v89, v89
	v_fmac_f32_e32 v66, v90, v90
	v_fmac_f32_e32 v66, v91, v91
	v_fmac_f32_e32 v66, v92, v92
	v_fmac_f32_e32 v66, v93, v93
	v_fmac_f32_e32 v66, v94, v94
	v_fmac_f32_e32 v66, v95, v95
	v_fmac_f32_e32 v66, v96, v96
	v_fmac_f32_e32 v66, v97, v97
	v_fmac_f32_e32 v66, v98, v98
	v_mul_f32_e32 v99, v24, v158
	v_fmac_f32_e32 v66, v99, v99
	v_mul_f32_e32 v100, v25, v158
	v_fmac_f32_e32 v66, v100, v100
	v_fmac_f32_e32 v66, v101, v101
	v_fmac_f32_e32 v66, v56, v56
	v_mul_f32_e32 v28, v28, v158
	v_fmac_f32_e32 v66, v28, v28
	v_mul_f32_e32 v29, v29, v158
	v_fmac_f32_e32 v66, v29, v29
	v_mul_f32_e32 v30, v30, v158
	v_fmac_f32_e32 v66, v30, v30
	v_mul_f32_e32 v31, v31, v158
	v_fmac_f32_e32 v66, v31, v31
	v_fmac_f32_e32 v66, v57, v57
	v_fmac_f32_e32 v66, v102, v102
	v_fmac_f32_e32 v66, v103, v103
	v_fmac_f32_e32 v66, v104, v104
	v_mul_f32_e32 v105, v4, v158
	v_fmac_f32_e32 v66, v105, v105
	v_mul_f32_e32 v106, v5, v158
	v_fmac_f32_e32 v66, v106, v106
	v_mul_f32_e32 v107, v6, v158
	v_fmac_f32_e32 v66, v107, v107
	v_mul_f32_e32 v108, v7, v158
	v_fmac_f32_e32 v66, v108, v108
	v_mul_f32_e32 v8, v8, v158
	v_fmac_f32_e32 v66, v8, v8
	v_mul_f32_e32 v9, v9, v158
	v_fmac_f32_e32 v66, v9, v9
	v_mul_f32_e32 v10, v10, v158
	v_fmac_f32_e32 v66, v10, v10
	v_mul_f32_e32 v11, v11, v158
	v_fmac_f32_e32 v66, v11, v11
	v_mul_f32_e32 v12, v12, v158
	v_fmac_f32_e32 v66, v12, v12
	v_mul_f32_e32 v13, v13, v158
	s_waitcnt vmcnt(0) lgkmcnt(0)
; DEV void epi_ukv(f32x16 (&acc)[1][8], const Params& P, int layer, int batch, int m0, int head, int wid, int r32, int hi, char* lds) {
;     ...
;       s += kr[b][r4].x * kr[b][r4].x + kr[b][r4].y * kr[b][r4].y + kr[b][r4].z * kr[b][r4].z + kr[b][r4].w * kr[b][r4].w;
;     }
;   s = swapsum(s);
;   const float inv = __builtin_amdgcn_rsqf(s * (1.f / 192.f) + EPS);
;   const float* g = WS{P.ws}.consts() + layer * 1024 + 512;
;   char* dst = slab + r32 * 400;
; #pragma unroll
;   for (int ni = 0; ni < 4; ++ni)
; #pragma unroll
;     for (int r4 = 0; r4 < 4; ++r4) {
;       const int c = ni * 32 + r4 * 8 + hi * 4;
;       const float4 gg = *reinterpret_cast<const float4*>(g + c);
;       const f32x16& a = acc[0][ni];
;       st4lds(dst, c, a[r4 * 4] * inv * gg.x, a[r4 * 4 + 1] * inv * gg.y, a[r4 * 4 + 2] * inv * gg.z, a[r4 * 4 + 3] * inv * gg.w);
;     }
	v_mul_f32_e32 v4, v49, v49
	v_fmac_f32_e32 v66, v13, v13
	v_mul_f32_e32 v14, v14, v158
	v_fmac_f32_e32 v4, v48, v48
	v_mul_f32_e32 v5, v41, v41
	v_fmac_f32_e32 v66, v14, v14
	v_mul_f32_e32 v15, v15, v158
	v_fmac_f32_e32 v4, v50, v50
	v_fmac_f32_e32 v5, v40, v40
	v_fmac_f32_e32 v66, v15, v15
	v_fmac_f32_e32 v4, v51, v51
	v_fmac_f32_e32 v5, v42, v42
	v_add_f32_e32 v4, v66, v4
	v_fmac_f32_e32 v5, v43, v43
	v_add_f32_e32 v4, v4, v5
	v_mul_f32_e32 v5, v37, v37
	v_fmac_f32_e32 v5, v36, v36
	v_fmac_f32_e32 v5, v38, v38
	v_fmac_f32_e32 v5, v39, v39
	v_add_f32_e32 v4, v4, v5
	v_mul_f32_e32 v5, v33, v33
	v_fmac_f32_e32 v5, v32, v32
	v_fmac_f32_e32 v5, v34, v34
	v_fmac_f32_e32 v5, v35, v35
	v_mov_b32_e32 v6, v53
	v_mov_b32_e32 v7, v45
	v_add_f32_e32 v24, v4, v5
	v_mov_b32_e32 v4, v52
	v_mov_b32_e32 v5, v44
	v_pk_mul_f32 v[6:7], v[6:7], v[6:7]
	v_lshlrev_b32_e32 v184, 5, v155
	v_pk_fma_f32 v[4:5], v[4:5], v[4:5], v[6:7]
	v_mov_b32_e32 v6, v54
	v_mov_b32_e32 v7, v46
	v_pk_fma_f32 v[4:5], v[6:7], v[6:7], v[4:5]
	v_mov_b32_e32 v6, v55
	v_mov_b32_e32 v7, v47
	v_pk_fma_f32 v[4:5], v[6:7], v[6:7], v[4:5]
	v_mov_b32_e32 v6, v21
	v_add_f32_e32 v4, v24, v4
	v_mov_b32_e32 v7, v17
	v_add_f32_e32 v24, v4, v5
	v_mov_b32_e32 v4, v20
	v_mov_b32_e32 v5, v16
	v_pk_mul_f32 v[6:7], v[6:7], v[6:7]
	s_nop 0
	v_pk_fma_f32 v[4:5], v[4:5], v[4:5], v[6:7]
	v_mov_b32_e32 v6, v22
	v_mov_b32_e32 v7, v18
	v_pk_fma_f32 v[4:5], v[6:7], v[6:7], v[4:5]
	v_mov_b32_e32 v6, v23
	v_mov_b32_e32 v7, v19
	v_pk_fma_f32 v[4:5], v[6:7], v[6:7], v[4:5]
	s_nop 0
	v_add_f32_e32 v4, v24, v4
	v_add_f32_e32 v4, v4, v5
	v_mov_b32_e32 v5, v4
	s_nop 1
	v_permlane32_swap_b32_e32 v4, v5
	v_add_f32_e32 v4, v4, v5
	v_fmamk_f32 v4, v4, 0x3baaaaab, v227
	v_rsq_f32_e32 v24, v4
	v_mul_u32_u24_e32 v4, 0x190, v154
	v_add3_u32 v25, v153, v4, v157
	v_mul_f32_e32 v5, v64, v24
	v_mul_f32_e32 v0, v0, v5
	v_mul_f32_e32 v5, v65, v24
	v_mul_f32_e32 v1, v1, v5
	v_mul_f32_e32 v5, v67, v24
	v_mul_f32_e32 v2, v2, v5
	v_mul_f32_e32 v5, v68, v24
	v_mul_f32_e32 v3, v3, v5
	v_cvt_pk_bf16_f32 v0, v0, v1
	v_cvt_pk_bf16_f32 v1, v2, v3
	ds_write_b64 v25, v[0:1]
	v_mul_f32_e32 v4, v69, v24
	v_mul_f32_e32 v5, v74, v24
	v_mul_f32_e32 v6, v62, v24
	v_mul_f32_e32 v7, v63, v24
	s_waitcnt vmcnt(0) lgkmcnt(0)
	v_mul_f32_e32 v0, v4, v194
	v_mul_f32_e32 v4, v70, v24
	v_mul_f32_e32 v1, v4, v195
	v_mul_f32_e32 v4, v71, v24
	v_mul_f32_e32 v2, v4, v196
	v_mul_f32_e32 v4, v72, v24
	v_mul_f32_e32 v3, v4, v197
	v_cvt_pk_bf16_f32 v0, v0, v1
	v_cvt_pk_bf16_f32 v1, v2, v3
	ds_write_b64 v25, v[0:1] offset:16
	v_mul_f32_e32 v4, v73, v24
	s_waitcnt vmcnt(0) lgkmcnt(0)
	v_mul_f32_e32 v0, v4, v198
	v_mul_f32_e32 v4, v58, v24
	v_mul_f32_e32 v1, v5, v199
	v_mul_f32_e32 v2, v4, v200
	v_mul_f32_e32 v4, v59, v24
	v_mul_f32_e32 v3, v4, v201
	v_cvt_pk_bf16_f32 v0, v0, v1
	v_cvt_pk_bf16_f32 v1, v2, v3
	ds_write_b64 v25, v[0:1] offset:32
	v_mul_f32_e32 v4, v60, v24
	v_mul_f32_e32 v5, v61, v24
	s_waitcnt vmcnt(0) lgkmcnt(0)
	v_mul_f32_e32 v0, v4, v202
	v_mul_f32_e32 v1, v5, v203
	v_mul_f32_e32 v2, v6, v204
	v_mul_f32_e32 v3, v7, v205
	v_cvt_pk_bf16_f32 v0, v0, v1
	v_cvt_pk_bf16_f32 v1, v2, v3
	ds_write_b64 v25, v[0:1] offset:48
	v_mul_f32_e32 v4, v75, v24
	v_mul_f32_e32 v5, v76, v24
	v_mul_f32_e32 v6, v77, v24
	v_mul_f32_e32 v7, v78, v24
	s_waitcnt vmcnt(0) lgkmcnt(0)
	v_mul_f32_e32 v0, v4, v206
	v_mul_f32_e32 v1, v5, v207
	v_mul_f32_e32 v2, v6, v208
	v_mul_f32_e32 v3, v7, v209
	v_cvt_pk_bf16_f32 v0, v0, v1
	v_cvt_pk_bf16_f32 v1, v2, v3
	ds_write_b64 v25, v[0:1] offset:64
	v_mul_f32_e32 v4, v79, v24
	v_mul_f32_e32 v5, v80, v24
	v_mul_f32_e32 v6, v81, v24
	v_mul_f32_e32 v7, v82, v24
	s_waitcnt vmcnt(0) lgkmcnt(0)
	v_mul_f32_e32 v0, v4, v210
	v_mul_f32_e32 v1, v5, v211
	v_mul_f32_e32 v2, v6, v212
	v_mul_f32_e32 v3, v7, v213
	v_cvt_pk_bf16_f32 v0, v0, v1
	v_cvt_pk_bf16_f32 v1, v2, v3
	ds_write_b64 v25, v[0:1] offset:80
	v_mul_f32_e32 v4, v83, v24
	v_mul_f32_e32 v5, v84, v24
	v_mul_f32_e32 v6, v85, v24
	v_mul_f32_e32 v7, v86, v24
	s_waitcnt vmcnt(0) lgkmcnt(0)
	v_mul_f32_e32 v0, v4, v214
	v_mul_f32_e32 v1, v5, v215
	v_mul_f32_e32 v2, v6, v216
	v_mul_f32_e32 v3, v7, v217
	v_cvt_pk_bf16_f32 v0, v0, v1
	v_cvt_pk_bf16_f32 v1, v2, v3
	ds_write_b64 v25, v[0:1] offset:96
	v_mul_f32_e32 v4, v87, v24
	v_mul_f32_e32 v5, v88, v24
	v_mul_f32_e32 v6, v89, v24
	v_mul_f32_e32 v7, v90, v24
	s_waitcnt vmcnt(0) lgkmcnt(0)
	v_mul_f32_e32 v0, v4, v218
	v_mul_f32_e32 v1, v5, v219
	v_mul_f32_e32 v2, v6, v220
	v_mul_f32_e32 v3, v7, v221
	v_cvt_pk_bf16_f32 v0, v0, v1
	v_cvt_pk_bf16_f32 v1, v2, v3
	ds_write_b64 v25, v[0:1] offset:112
	v_mul_f32_e32 v4, v91, v24
	v_mul_f32_e32 v5, v92, v24
	v_mul_f32_e32 v6, v93, v24
	v_mul_f32_e32 v7, v94, v24
	s_waitcnt vmcnt(0) lgkmcnt(0)
	v_mul_f32_e32 v0, v4, v222
	v_mul_f32_e32 v1, v5, v223
	v_mul_f32_e32 v2, v6, v224
	v_mul_f32_e32 v3, v7, v225
	v_cvt_pk_bf16_f32 v0, v0, v1
	v_cvt_pk_bf16_f32 v1, v2, v3
	ds_write_b64 v25, v[0:1] offset:128
	v_mul_f32_e32 v4, v95, v24
	v_mul_f32_e32 v5, v96, v24
	v_mul_f32_e32 v6, v97, v24
	v_mul_f32_e32 v7, v98, v24
	s_waitcnt vmcnt(0) lgkmcnt(0)
	v_mul_f32_e32 v0, v4, v232
	v_mul_f32_e32 v1, v5, v233
	v_mul_f32_e32 v2, v6, v234
	v_mul_f32_e32 v3, v7, v235
	v_cvt_pk_bf16_f32 v0, v0, v1
	v_cvt_pk_bf16_f32 v1, v2, v3
	ds_write_b64 v25, v[0:1] offset:144
	v_mul_f32_e32 v4, v99, v24
	v_mul_f32_e32 v5, v100, v24
	v_mul_f32_e32 v6, v101, v24
	v_mul_f32_e32 v7, v56, v24
	s_waitcnt vmcnt(0) lgkmcnt(0)
; DEV void epi_ukv(f32x16 (&acc)[1][8], const Params& P, int layer, int batch, int m0, int head, int wid, int r32, int hi, char* lds) {
;     ...
; #pragma unroll
;   for (int ni = 0; ni < 4; ++ni)
; #pragma unroll
;     for (int r4 = 0; r4 < 4; ++r4) {
;       const int c = ni * 32 + r4 * 8 + hi * 4;
;       const float4 gg = *reinterpret_cast<const float4*>(g + c);
;       const f32x16& a = acc[0][ni];
;       st4lds(dst, c, a[r4 * 4] * inv * gg.x, a[r4 * 4 + 1] * inv * gg.y, a[r4 * 4 + 2] * inv * gg.z, a[r4 * 4 + 3] * inv * gg.w);
;     }
;   const int pos = batch ? t : (t & 4095);
;   const float2* rp = WS{P.ws}.rope() + (long)pos * 32;
; #pragma unroll
;   for (int r4 = 0; r4 < 4; ++r4) {
;     const int i = r4 * 8 + hi * 4;
;     const float4 g1 = *reinterpret_cast<const float4*>(g + 128 + i), g2 = *reinterpret_cast<const float4*>(g + 160 + i);
;     const float4 cs01 = *reinterpret_cast<const float4*>(rp + i), cs23 = *reinterpret_cast<const float4*>(rp + i + 2);
;     const float x1[4] = {kr[0][r4].x * inv * g1.x, kr[0][r4].y * inv * g1.y, kr[0][r4].z * inv * g1.z, kr[0][r4].w * inv * g1.w};
;     const float x2[4] = {kr[1][r4].x * inv * g2.x, kr[1][r4].y * inv * g2.y, kr[1][r4].z * inv * g2.z, kr[1][r4].w * inv * g2.w};
;     const float cc[4] = {cs01.x, cs01.z, cs23.x, cs23.z}, sn[4] = {cs01.y, cs01.w, cs23.y, cs23.w};
;     st4lds(dst, 128 + i, x1[0] * cc[0] - x2[0] * sn[0], x1[1] * cc[1] - x2[1] * sn[1], x1[2] * cc[2] - x2[2] * sn[2], x1[3] * cc[3] - x2[3] * sn[3]);
;     st4lds(dst, 160 + i, x1[0] * sn[0] + x2[0] * cc[0], x1[1] * sn[1] + x2[1] * cc[1], x1[2] * sn[2] + x2[2] * cc[2], x1[3] * sn[3] + x2[3] * cc[3]);
	v_mul_f32_e32 v0, v4, v236
	v_mul_f32_e32 v1, v5, v237
	v_mul_f32_e32 v2, v6, v238
	v_mul_f32_e32 v3, v7, v239
	v_cvt_pk_bf16_f32 v0, v0, v1
	v_cvt_pk_bf16_f32 v1, v2, v3
	ds_write_b64 v25, v[0:1] offset:160
	v_mul_f32_e32 v4, v28, v24
	v_mul_f32_e32 v5, v29, v24
	v_mul_f32_e32 v6, v30, v24
	v_mul_f32_e32 v7, v31, v24
	v_mov_b32_e32 v30, v48
	v_mov_b32_e32 v31, v52
	v_mov_b32_e32 v52, v49
	v_mov_b32_e32 v48, v50
	v_mov_b32_e32 v49, v54
	v_mov_b32_e32 v54, v51
	v_pk_mul_f32 v[30:31], v[30:31], v[24:25] op_sel_hi:[1,0]
	v_pk_mul_f32 v[50:51], v[52:53], v[24:25] op_sel_hi:[1,0]
	v_pk_mul_f32 v[48:49], v[48:49], v[24:25] op_sel_hi:[1,0]
	v_pk_mul_f32 v[52:53], v[54:55], v[24:25] op_sel_hi:[1,0]
	s_waitcnt vmcnt(0) lgkmcnt(0)
	v_mul_f32_e32 v0, v4, v240
	v_mul_f32_e32 v1, v5, v241
	v_mul_f32_e32 v2, v6, v242
	v_mul_f32_e32 v3, v7, v243
	v_cvt_pk_bf16_f32 v0, v0, v1
	v_cvt_pk_bf16_f32 v1, v2, v3
	ds_write_b64 v25, v[0:1] offset:176
	v_mul_f32_e32 v4, v57, v24
	v_mul_f32_e32 v5, v102, v24
	v_mul_f32_e32 v6, v103, v24
	v_mul_f32_e32 v7, v104, v24
	s_waitcnt vmcnt(0) lgkmcnt(0)
	v_mul_f32_e32 v0, v4, v244
	v_mul_f32_e32 v1, v5, v245
	v_mul_f32_e32 v2, v6, v246
	v_mul_f32_e32 v3, v7, v247
	v_cvt_pk_bf16_f32 v0, v0, v1
	v_cvt_pk_bf16_f32 v1, v2, v3
	ds_write_b64 v25, v[0:1] offset:192
	v_mul_f32_e32 v4, v105, v24
	v_mul_f32_e32 v5, v106, v24
	v_mul_f32_e32 v6, v107, v24
	v_mul_f32_e32 v7, v108, v24
	s_waitcnt vmcnt(0) lgkmcnt(0)
	v_mul_f32_e32 v0, v4, v248
	v_mul_f32_e32 v1, v5, v249
	v_mul_f32_e32 v2, v6, v250
	v_mul_f32_e32 v3, v7, v251
	v_cvt_pk_bf16_f32 v0, v0, v1
	v_cvt_pk_bf16_f32 v1, v2, v3
	ds_write_b64 v25, v[0:1] offset:208
	v_mul_f32_e32 v4, v8, v24
	v_mul_f32_e32 v5, v9, v24
	v_mul_f32_e32 v6, v10, v24
	v_mul_f32_e32 v7, v11, v24
	v_bitop3_b32 v8, v148, s2, v154 bitop3:0xc8
	v_cndmask_b32_e64 v8, v150, v8, s[26:27]
	v_ashrrev_i32_e32 v9, 31, v8
	v_lshlrev_b64 v[8:9], 8, v[8:9]
	v_lshl_add_u64 v[8:9], s[12:13], 0, v[8:9]
	v_lshl_add_u64 v[28:29], v[8:9], 0, v[184:185]
	s_waitcnt vmcnt(0) lgkmcnt(0)
	v_mul_f32_e32 v0, v4, v170
	v_mul_f32_e32 v1, v5, v171
	v_mul_f32_e32 v2, v6, v172
	v_mul_f32_e32 v3, v7, v173
	v_cvt_pk_bf16_f32 v0, v0, v1
	v_cvt_pk_bf16_f32 v1, v2, v3
	ds_write_b64 v25, v[0:1] offset:224
	v_mul_f32_e32 v4, v12, v24
	v_mul_f32_e32 v5, v13, v24
	v_mul_f32_e32 v6, v14, v24
	v_mul_f32_e32 v7, v15, v24
	s_waitcnt vmcnt(0) lgkmcnt(0)
	v_mul_f32_e32 v0, v4, v174
	v_mul_f32_e32 v1, v5, v175
	v_mul_f32_e32 v2, v6, v176
	v_mul_f32_e32 v3, v7, v177
	v_cvt_pk_bf16_f32 v0, v0, v1
	v_cvt_pk_bf16_f32 v1, v2, v3
	ds_write_b64 v25, v[0:1] offset:240
	flat_load_dwordx4 v[0:3], v[26:27] offset:2560
	flat_load_dwordx4 v[4:7], v[26:27] offset:2688
	flat_load_dwordx4 v[8:11], v[28:29]
	flat_load_dwordx4 v[12:15], v[28:29] offset:16
	s_waitcnt vmcnt(0) lgkmcnt(0)
	v_mov_b32_e32 v54, v0
	v_mov_b32_e32 v55, v4
	v_mov_b32_e32 v4, v1
	v_mov_b32_e32 v0, v2
	v_mov_b32_e32 v1, v6
	v_mov_b32_e32 v6, v3
	v_pk_mul_f32 v[2:3], v[30:31], v[54:55]
	v_pk_mul_f32 v[4:5], v[50:51], v[4:5]
	v_pk_mul_f32 v[0:1], v[48:49], v[0:1]
	v_pk_mul_f32 v[6:7], v[52:53], v[6:7]
	v_pk_mul_f32 v[30:31], v[2:3], v[8:9]
	v_pk_mul_f32 v[48:49], v[4:5], v[10:11]
	v_pk_mul_f32 v[50:51], v[0:1], v[12:13]
	v_pk_mul_f32 v[52:53], v[6:7], v[14:15]
	v_pk_mul_f32 v[2:3], v[2:3], v[8:9] op_sel:[1,0] op_sel_hi:[0,1]
	v_pk_mul_f32 v[4:5], v[4:5], v[10:11] op_sel:[1,0] op_sel_hi:[0,1]
	v_pk_mul_f32 v[0:1], v[0:1], v[12:13] op_sel:[1,0] op_sel_hi:[0,1]
	v_pk_mul_f32 v[6:7], v[6:7], v[14:15] op_sel:[1,0] op_sel_hi:[0,1]
	v_sub_f32_e32 v8, v30, v31
	v_sub_f32_e32 v9, v48, v49
	v_sub_f32_e32 v10, v50, v51
	v_sub_f32_e32 v11, v52, v53
	v_add_f32_e32 v2, v2, v3
	v_add_f32_e32 v3, v4, v5
	v_add_f32_e32 v4, v0, v1
	v_cvt_pk_bf16_f32 v0, v8, v9
	v_cvt_pk_bf16_f32 v1, v10, v11
	v_add_f32_e32 v5, v6, v7
	ds_write_b64 v25, v[0:1] offset:256
	v_cvt_pk_bf16_f32 v0, v2, v3
	v_cvt_pk_bf16_f32 v1, v4, v5
	ds_write_b64 v25, v[0:1] offset:320
	flat_load_dwordx4 v[0:3], v[26:27] offset:2592
	flat_load_dwordx4 v[4:7], v[26:27] offset:2720
	flat_load_dwordx4 v[8:11], v[28:29] offset:64
	flat_load_dwordx4 v[12:15], v[28:29] offset:80
	v_mov_b32_e32 v30, v40
	v_mov_b32_e32 v31, v44
	v_mov_b32_e32 v44, v41
	v_mov_b32_e32 v40, v42
	v_mov_b32_e32 v41, v46
	v_mov_b32_e32 v46, v43
	v_pk_mul_f32 v[30:31], v[30:31], v[24:25] op_sel_hi:[1,0]
	v_pk_mul_f32 v[42:43], v[44:45], v[24:25] op_sel_hi:[1,0]
	v_pk_mul_f32 v[40:41], v[40:41], v[24:25] op_sel_hi:[1,0]
	v_pk_mul_f32 v[44:45], v[46:47], v[24:25] op_sel_hi:[1,0]
	s_waitcnt vmcnt(0) lgkmcnt(0)
; #define LDSP(T) __attribute__((address_space(3))) T*
; template <int NCH, int STRIDE> DEV void slab_flush(char* slab, u16* grow0, int gstride, int lane) {
;   asm volatile("s_waitcnt lgkmcnt(0)" ::: "memory");
; #pragma unroll
;   for (int i = 0; i < NCH / 2; ++i) {
;     const int q = i * 64 + lane, row = q / NCH, cc = q - row * NCH;
;     const u32x4 v = *(LDSP(const u32x4))(slab + row * STRIDE + cc * 16);
;     *reinterpret_cast<u32x4*>(grow0 + (long)row * gstride + cc * 8) = v;
; DEV void epi_ukv(f32x16 (&acc)[1][8], const Params& P, int layer, int batch, int m0, int head, int wid, int r32, int hi, char* lds) {
;     ...
; #pragma unroll
;   for (int r4 = 0; r4 < 4; ++r4) {
;     const int i = r4 * 8 + hi * 4;
;     const float4 g1 = *reinterpret_cast<const float4*>(g + 128 + i), g2 = *reinterpret_cast<const float4*>(g + 160 + i);
;     const float4 cs01 = *reinterpret_cast<const float4*>(rp + i), cs23 = *reinterpret_cast<const float4*>(rp + i + 2);
;     const float x1[4] = {kr[0][r4].x * inv * g1.x, kr[0][r4].y * inv * g1.y, kr[0][r4].z * inv * g1.z, kr[0][r4].w * inv * g1.w};
;     const float x2[4] = {kr[1][r4].x * inv * g2.x, kr[1][r4].y * inv * g2.y, kr[1][r4].z * inv * g2.z, kr[1][r4].w * inv * g2.w};
;     const float cc[4] = {cs01.x, cs01.z, cs23.x, cs23.z}, sn[4] = {cs01.y, cs01.w, cs23.y, cs23.w};
;     st4lds(dst, 128 + i, x1[0] * cc[0] - x2[0] * sn[0], x1[1] * cc[1] - x2[1] * sn[1], x1[2] * cc[2] - x2[2] * sn[2], x1[3] * cc[3] - x2[3] * sn[3]);
;     st4lds(dst, 160 + i, x1[0] * sn[0] + x2[0] * cc[0], x1[1] * sn[1] + x2[1] * cc[1], x1[2] * sn[2] + x2[2] * cc[2], x1[3] * sn[3] + x2[3] * cc[3]);
;   }
	v_mov_b32_e32 v46, v0
	v_mov_b32_e32 v47, v4
	v_mov_b32_e32 v4, v1
	v_mov_b32_e32 v0, v2
	v_mov_b32_e32 v1, v6
	v_mov_b32_e32 v6, v3
	v_pk_mul_f32 v[2:3], v[30:31], v[46:47]
	v_pk_mul_f32 v[4:5], v[42:43], v[4:5]
	v_pk_mul_f32 v[0:1], v[40:41], v[0:1]
	v_pk_mul_f32 v[6:7], v[44:45], v[6:7]
	v_pk_mul_f32 v[30:31], v[2:3], v[8:9]
	v_pk_mul_f32 v[40:41], v[4:5], v[10:11]
	v_pk_mul_f32 v[42:43], v[0:1], v[12:13]
	v_pk_mul_f32 v[44:45], v[6:7], v[14:15]
	v_pk_mul_f32 v[2:3], v[2:3], v[8:9] op_sel:[1,0] op_sel_hi:[0,1]
	v_pk_mul_f32 v[4:5], v[4:5], v[10:11] op_sel:[1,0] op_sel_hi:[0,1]
	v_pk_mul_f32 v[0:1], v[0:1], v[12:13] op_sel:[1,0] op_sel_hi:[0,1]
	v_pk_mul_f32 v[6:7], v[6:7], v[14:15] op_sel:[1,0] op_sel_hi:[0,1]
	v_sub_f32_e32 v8, v30, v31
	v_sub_f32_e32 v9, v40, v41
	v_sub_f32_e32 v10, v42, v43
	v_sub_f32_e32 v11, v44, v45
	v_add_f32_e32 v2, v2, v3
	v_add_f32_e32 v3, v4, v5
	v_add_f32_e32 v4, v0, v1
	v_cvt_pk_bf16_f32 v0, v8, v9
	v_cvt_pk_bf16_f32 v1, v10, v11
	v_add_f32_e32 v5, v6, v7
	ds_write_b64 v25, v[0:1] offset:272
	v_cvt_pk_bf16_f32 v0, v2, v3
	v_cvt_pk_bf16_f32 v1, v4, v5
	ds_write_b64 v25, v[0:1] offset:336
	flat_load_dwordx4 v[8:11], v[26:27] offset:2624
	flat_load_dwordx4 v[4:7], v[26:27] offset:2752
	flat_load_dwordx4 v[0:3], v[28:29] offset:128
	flat_load_dwordx4 v[12:15], v[28:29] offset:144
	v_and_b32_e32 v40, 63, v152
	v_mul_lo_u16_e32 v41, 43, v40
	v_or_b32_e32 v42, 64, v40
	v_or_b32_e32 v43, 0x80, v40
	v_lshrrev_b16_e32 v41, 10, v41
	v_mul_lo_u16_e32 v53, 43, v42
	v_mul_lo_u16_e32 v54, 0xab, v43
	v_or_b32_e32 v44, 0xc0, v40
	v_or_b32_e32 v45, 0x100, v40
	v_or_b32_e32 v46, 0x180, v40
	v_or_b32_e32 v47, 0x140, v40
	v_or_b32_e32 v48, 0x200, v40
	v_or_b32_e32 v49, 0x1c0, v40
	v_or_b32_e32 v50, 0x280, v40
	v_or_b32_e32 v51, 0x240, v40
	v_or_b32_e32 v52, 0x2c0, v40
	v_mad_i32_i24 v40, v41, s58, v40
	v_mul_u32_u24_e32 v64, 0x190, v41
	v_mul_u32_u24_e32 v65, 0x300, v41
	v_lshrrev_b16_e32 v41, 10, v53
	v_lshrrev_b16_e32 v53, 12, v54
	v_mad_i32_i24 v69, v41, s58, v42
	v_mad_i32_i24 v72, v53, s58, v43
	v_mov_b32_e32 v42, v36
	v_mov_b32_e32 v43, v20
	v_mov_b32_e32 v20, v37
	v_mov_b32_e32 v36, v38
	v_mov_b32_e32 v37, v22
	v_mov_b32_e32 v22, v39
	v_pk_mul_f32 v[38:39], v[42:43], v[24:25] op_sel_hi:[1,0]
	v_pk_mul_f32 v[20:21], v[20:21], v[24:25] op_sel_hi:[1,0]
	v_pk_mul_f32 v[36:37], v[36:37], v[24:25] op_sel_hi:[1,0]
	v_pk_mul_f32 v[22:23], v[22:23], v[24:25] op_sel_hi:[1,0]
	v_mul_lo_u16_e32 v55, 0xab, v44
	v_mul_u32_u24_e32 v56, 0xaab, v45
	v_mul_u32_u24_e32 v57, 0xaab, v47
	v_mul_u32_u24_e32 v58, 0xaab, v46
	v_mul_u32_u24_e32 v59, 0xaab, v49
	v_mul_u32_u24_e32 v60, 0xaab, v48
	v_mul_u32_u24_e32 v61, 0xaab, v51
	v_mul_u32_u24_e32 v62, 0xaab, v50
	v_mov_b64_e32 v[30:31], s[70:71]
	v_mul_u32_u24_e32 v63, 0xaab, v52
	v_lshrrev_b16_e32 v54, 12, v55
	v_lshrrev_b32_e32 v55, 16, v56
	v_lshrrev_b32_e32 v56, 16, v57
	v_lshrrev_b32_e32 v66, 16, v58
	v_perm_b32 v57, v58, v57, s44
	v_lshrrev_b32_e32 v58, 16, v59
	v_lshrrev_b32_e32 v67, 16, v60
	v_perm_b32 v59, v60, v59, s44
	v_lshrrev_b32_e32 v60, 16, v61
	v_lshrrev_b32_e32 v68, 16, v62
	v_mad_i64_i32 v[30:31], s[2:3], v148, s39, v[30:31]
	v_perm_b32 v61, v62, v61, s44
	v_lshrrev_b32_e32 v62, 16, v63
	v_lshlrev_b32_e32 v63, 4, v40
	v_mad_i32_i24 v48, v67, s58, v48
	v_mad_i32_i24 v51, v60, s58, v51
	v_mad_i32_i24 v50, v68, s58, v50
	v_mad_i32_i24 v52, v62, s58, v52
	v_lshlrev_b32_e32 v75, 4, v48
	v_lshlrev_b32_e32 v77, 4, v51
	v_lshlrev_b32_e32 v78, 4, v50
	v_lshlrev_b32_e32 v40, 3, v40
	v_lshlrev_b32_e32 v184, 1, v65
	v_mul_u32_u24_e32 v70, 0x190, v41
	v_mul_u32_u24_e32 v71, 0x300, v41
	v_ashrrev_i32_e32 v41, 31, v40
	v_lshlrev_b32_e32 v79, 4, v52
	s_waitcnt vmcnt(0) lgkmcnt(0)
	v_mov_b32_e32 v42, v8
	v_mov_b32_e32 v43, v4
	v_mov_b32_e32 v4, v9
	v_mov_b32_e32 v8, v10
	v_mov_b32_e32 v9, v6
	v_mov_b32_e32 v6, v11
	v_pk_mul_f32 v[10:11], v[38:39], v[42:43]
	v_pk_mul_f32 v[4:5], v[20:21], v[4:5]
	v_pk_mul_f32 v[8:9], v[36:37], v[8:9]
	v_pk_mul_f32 v[6:7], v[22:23], v[6:7]
	v_pk_mul_f32 v[20:21], v[10:11], v[0:1]
	v_pk_mul_f32 v[22:23], v[4:5], v[2:3]
	v_pk_mul_f32 v[36:37], v[8:9], v[12:13]
	v_pk_mul_f32 v[38:39], v[6:7], v[14:15]
	v_pk_mul_f32 v[0:1], v[10:11], v[0:1] op_sel:[1,0] op_sel_hi:[0,1]
	v_pk_mul_f32 v[2:3], v[4:5], v[2:3] op_sel:[1,0] op_sel_hi:[0,1]
	v_pk_mul_f32 v[4:5], v[8:9], v[12:13] op_sel:[1,0] op_sel_hi:[0,1]
	v_pk_mul_f32 v[6:7], v[6:7], v[14:15] op_sel:[1,0] op_sel_hi:[0,1]
	v_sub_f32_e32 v8, v20, v21
	v_sub_f32_e32 v9, v22, v23
	v_sub_f32_e32 v10, v36, v37
	v_sub_f32_e32 v11, v38, v39
	v_add_f32_e32 v12, v0, v1
	v_cvt_pk_bf16_f32 v0, v8, v9
	v_cvt_pk_bf16_f32 v1, v10, v11
	v_add_f32_e32 v2, v2, v3
	v_add_f32_e32 v3, v4, v5
	v_add_f32_e32 v4, v6, v7
	ds_write_b64 v25, v[0:1] offset:288
	v_cvt_pk_bf16_f32 v0, v12, v2
	v_cvt_pk_bf16_f32 v1, v3, v4
	ds_write_b64 v25, v[0:1] offset:352
	flat_load_dwordx4 v[0:3], v[26:27] offset:2656
	flat_load_dwordx4 v[4:7], v[26:27] offset:2784
	flat_load_dwordx4 v[8:11], v[28:29] offset:192
	flat_load_dwordx4 v[12:15], v[28:29] offset:208
	v_mad_i32_i24 v23, v54, s58, v44
	v_mad_i32_i24 v36, v55, s58, v45
	v_mad_i32_i24 v38, v56, s58, v47
	v_mad_i32_i24 v42, v66, s58, v46
	v_mad_i32_i24 v44, v58, s58, v49
	v_pk_mul_lo_u16 v46, v59, s37 op_sel_hi:[1,0]
	v_mul_u32_u24_e32 v39, 0x190, v55
	v_mul_u32_u24_e32 v45, 0x300, v55
	v_pk_mul_lo_u16 v29, v57, s37 op_sel_hi:[1,0]
	v_mul_u32_u24_e32 v47, 0x300, v56
	v_mul_u32_u24_e32 v55, 0x300, v67
	v_pk_mul_lo_u16 v56, v61, s37 op_sel_hi:[1,0]
	v_mul_u32_u24_e32 v57, 0x300, v60
	v_mul_u32_u24_e32 v59, 0x190, v62
	v_mul_u32_u24_e32 v60, 0x300, v62
	v_lshl_add_u64 v[20:21], v[30:31], 0, s[22:23]
; #define LDSP(T) __attribute__((address_space(3))) T*
; template <int NCH, int STRIDE> DEV void slab_flush(char* slab, u16* grow0, int gstride, int lane) {
;   asm volatile("s_waitcnt lgkmcnt(0)" ::: "memory");
; #pragma unroll
;   for (int i = 0; i < NCH / 2; ++i) {
;     const int q = i * 64 + lane, row = q / NCH, cc = q - row * NCH;
;     const u32x4 v = *(LDSP(const u32x4))(slab + row * STRIDE + cc * 16);
;     *reinterpret_cast<u32x4*>(grow0 + (long)row * gstride + cc * 8) = v;
;   }
;   asm volatile("s_waitcnt lgkmcnt(0)" ::: "memory");
; }
; DEV void epi_ukv(f32x16 (&acc)[1][8], const Params& P, int layer, int batch, int m0, int head, int wid, int r32, int hi, char* lds) {
;     ...
; #pragma unroll
;   for (int r4 = 0; r4 < 4; ++r4) {
;     const int i = r4 * 8 + hi * 4;
;     const float4 g1 = *reinterpret_cast<const float4*>(g + 128 + i), g2 = *reinterpret_cast<const float4*>(g + 160 + i);
;     const float4 cs01 = *reinterpret_cast<const float4*>(rp + i), cs23 = *reinterpret_cast<const float4*>(rp + i + 2);
;     const float x1[4] = {kr[0][r4].x * inv * g1.x, kr[0][r4].y * inv * g1.y, kr[0][r4].z * inv * g1.z, kr[0][r4].w * inv * g1.w};
;     const float x2[4] = {kr[1][r4].x * inv * g2.x, kr[1][r4].y * inv * g2.y, kr[1][r4].z * inv * g2.z, kr[1][r4].w * inv * g2.w};
;     const float cc[4] = {cs01.x, cs01.z, cs23.x, cs23.z}, sn[4] = {cs01.y, cs01.w, cs23.y, cs23.w};
;     st4lds(dst, 128 + i, x1[0] * cc[0] - x2[0] * sn[0], x1[1] * cc[1] - x2[1] * sn[1], x1[2] * cc[2] - x2[2] * sn[2], x1[3] * cc[3] - x2[3] * sn[3]);
;     st4lds(dst, 160 + i, x1[0] * sn[0] + x2[0] * cc[0], x1[1] * sn[1] + x2[1] * cc[1], x1[2] * sn[2] + x2[2] * cc[2], x1[3] * sn[3] + x2[3] * cc[3]);
;   }
;   slab_flush<24, 400>(slab, WS{P.ws}.KB() + (long)(m0 + wid * 32) * 768 + head * 192, 768, hi * 32 + r32);
	v_add3_u32 v61, v153, v64, v63
	v_lshlrev_b32_e32 v31, 4, v69
	v_lshlrev_b32_e32 v22, 3, v69
	v_lshlrev_b32_e32 v62, 4, v72
	v_lshlrev_b32_e32 v26, 3, v72
	v_lshlrev_b32_e32 v64, 4, v36
	v_lshlrev_b32_e32 v30, 3, v36
	v_lshlrev_b32_e32 v67, 4, v38
	v_lshlrev_b32_e32 v36, 3, v38
	v_lshlrev_b32_e32 v69, 4, v42
	v_lshlrev_b32_e32 v38, 3, v42
	v_and_b32_e32 v72, 0xfff0, v46
	v_lshlrev_b32_e32 v73, 4, v44
	v_lshlrev_b32_e32 v42, 3, v44
	v_lshrrev_b32_e32 v74, 16, v46
	v_lshlrev_b32_e32 v44, 3, v48
	v_lshlrev_b32_e32 v46, 3, v51
	v_lshlrev_b32_e32 v48, 3, v50
	v_mov_b32_e32 v50, v32
	v_mov_b32_e32 v51, v16
	v_mov_b32_e32 v16, v33
	v_mov_b32_e32 v32, v34
	v_mov_b32_e32 v33, v18
	v_mov_b32_e32 v18, v35
	v_pk_mul_f32 v[34:35], v[50:51], v[24:25] op_sel_hi:[1,0]
	v_pk_mul_f32 v[16:17], v[16:17], v[24:25] op_sel_hi:[1,0]
	v_pk_mul_f32 v[32:33], v[32:33], v[24:25] op_sel_hi:[1,0]
	v_pk_mul_f32 v[18:19], v[18:19], v[24:25] op_sel_hi:[1,0]
	v_add3_u32 v70, v153, v70, v31
	v_lshlrev_b32_e32 v63, 4, v23
	v_lshlrev_b32_e32 v28, 3, v23
	v_ashrrev_i32_e32 v23, 31, v22
	v_mul_u32_u24_e32 v27, 0x190, v53
	v_add3_u32 v62, v153, v27, v62
	v_mul_u32_u24_e32 v43, 0x300, v53
	v_ashrrev_i32_e32 v27, 31, v26
	v_mul_u32_u24_e32 v37, 0x190, v54
	v_add3_u32 v63, v153, v37, v63
	v_mul_u32_u24_e32 v53, 0x300, v54
	v_mul_u32_u24_e32 v54, 0x300, v66
	v_mul_u32_u24_e32 v49, 0x300, v58
	v_mul_u32_u24_e32 v58, 0x300, v68
	v_and_b32_e32 v66, 0xfff0, v29
	v_lshrrev_b32_e32 v68, 16, v29
	v_ashrrev_i32_e32 v29, 31, v28
	v_add3_u32 v64, v153, v39, v64
	v_ashrrev_i32_e32 v31, 31, v30
	v_add3_u32 v66, v153, v66, v67
	v_ashrrev_i32_e32 v37, 31, v36
	v_ashrrev_i32_e32 v39, 31, v38
	v_and_b32_e32 v76, 0xfff0, v56
	v_lshrrev_b32_e32 v56, 16, v56
	s_waitcnt vmcnt(0) lgkmcnt(0)
	v_mov_b32_e32 v50, v0
	v_mov_b32_e32 v51, v4
	v_mov_b32_e32 v4, v1
	v_mov_b32_e32 v0, v2
	v_mov_b32_e32 v1, v6
	v_mov_b32_e32 v6, v3
	v_pk_mul_f32 v[2:3], v[34:35], v[50:51]
	v_pk_mul_f32 v[4:5], v[16:17], v[4:5]
	v_pk_mul_f32 v[0:1], v[32:33], v[0:1]
	v_pk_mul_f32 v[6:7], v[18:19], v[6:7]
	v_pk_mul_f32 v[16:17], v[2:3], v[8:9]
	v_pk_mul_f32 v[18:19], v[4:5], v[10:11]
	v_pk_mul_f32 v[32:33], v[0:1], v[12:13]
	v_pk_mul_f32 v[34:35], v[6:7], v[14:15]
	v_pk_mul_f32 v[2:3], v[2:3], v[8:9] op_sel:[1,0] op_sel_hi:[0,1]
	v_pk_mul_f32 v[4:5], v[4:5], v[10:11] op_sel:[1,0] op_sel_hi:[0,1]
	v_pk_mul_f32 v[0:1], v[0:1], v[12:13] op_sel:[1,0] op_sel_hi:[0,1]
	v_pk_mul_f32 v[6:7], v[6:7], v[14:15] op_sel:[1,0] op_sel_hi:[0,1]
	v_sub_f32_e32 v8, v16, v17
	v_sub_f32_e32 v9, v18, v19
	v_sub_f32_e32 v10, v32, v33
	v_sub_f32_e32 v11, v34, v35
	v_add_f32_e32 v2, v2, v3
	v_add_f32_e32 v3, v4, v5
	v_add_f32_e32 v4, v0, v1
	v_cvt_pk_bf16_f32 v0, v8, v9
	v_cvt_pk_bf16_f32 v1, v10, v11
	v_add_f32_e32 v5, v6, v7
	ds_write_b64 v25, v[0:1] offset:304
	v_cvt_pk_bf16_f32 v0, v2, v3
	v_cvt_pk_bf16_f32 v1, v4, v5
	ds_write_b64 v25, v[0:1] offset:368
	s_waitcnt lgkmcnt(0)
	ds_read_b128 v[0:3], v61
	v_lshl_add_u64 v[4:5], v[20:21], 0, v[184:185]
	v_lshl_add_u64 v[4:5], v[40:41], 1, v[4:5]
	v_lshlrev_b32_e32 v184, 1, v71
	v_add3_u32 v6, v153, v68, v69
	s_waitcnt lgkmcnt(0)
	flat_store_dwordx4 v[4:5], v[0:3]
	ds_read_b128 v[0:3], v70
	v_lshl_add_u64 v[4:5], v[20:21], 0, v[184:185]
	v_lshl_add_u64 v[4:5], v[22:23], 1, v[4:5]
	v_lshlrev_b32_e32 v184, 1, v43
	v_add3_u32 v7, v153, v72, v73
	s_waitcnt lgkmcnt(0)
	flat_store_dwordx4 v[4:5], v[0:3]
	ds_read_b128 v[0:3], v62
	v_lshl_add_u64 v[4:5], v[20:21], 0, v[184:185]
	v_lshl_add_u64 v[4:5], v[26:27], 1, v[4:5]
	v_lshlrev_b32_e32 v184, 1, v53
	v_ashrrev_i32_e32 v43, 31, v42
	s_waitcnt lgkmcnt(0)
	flat_store_dwordx4 v[4:5], v[0:3]
	ds_read_b128 v[0:3], v63
	v_lshl_add_u64 v[4:5], v[20:21], 0, v[184:185]
	v_lshl_add_u64 v[4:5], v[28:29], 1, v[4:5]
	v_lshlrev_b32_e32 v184, 1, v45
	v_add3_u32 v8, v153, v74, v75
	s_waitcnt lgkmcnt(0)
	flat_store_dwordx4 v[4:5], v[0:3]
	ds_read_b128 v[0:3], v64
	v_lshl_add_u64 v[4:5], v[20:21], 0, v[184:185]
	v_lshl_add_u64 v[4:5], v[30:31], 1, v[4:5]
	v_lshlrev_b32_e32 v184, 1, v47
	v_ashrrev_i32_e32 v45, 31, v44
	s_waitcnt lgkmcnt(0)
	flat_store_dwordx4 v[4:5], v[0:3]
	ds_read_b128 v[0:3], v66
	v_lshl_add_u64 v[4:5], v[20:21], 0, v[184:185]
	v_lshl_add_u64 v[4:5], v[36:37], 1, v[4:5]
	v_lshlrev_b32_e32 v184, 1, v54
	v_ashrrev_i32_e32 v47, 31, v46
	s_waitcnt lgkmcnt(0)
	flat_store_dwordx4 v[4:5], v[0:3]
	ds_read_b128 v[0:3], v6
	v_lshl_add_u64 v[4:5], v[20:21], 0, v[184:185]
	v_lshl_add_u64 v[4:5], v[38:39], 1, v[4:5]
	v_lshlrev_b32_e32 v184, 1, v49
	v_add3_u32 v6, v153, v76, v77
	s_waitcnt lgkmcnt(0)
	flat_store_dwordx4 v[4:5], v[0:3]
	ds_read_b128 v[0:3], v7
	v_lshl_add_u64 v[4:5], v[20:21], 0, v[184:185]
	v_lshl_add_u64 v[4:5], v[42:43], 1, v[4:5]
	v_lshlrev_b32_e32 v184, 1, v55
	v_add3_u32 v7, v153, v56, v78
	s_waitcnt lgkmcnt(0)
	flat_store_dwordx4 v[4:5], v[0:3]
	ds_read_b128 v[0:3], v8
	v_lshl_add_u64 v[4:5], v[20:21], 0, v[184:185]
	v_lshl_add_u64 v[4:5], v[44:45], 1, v[4:5]
	v_lshlrev_b32_e32 v184, 1, v57
	v_ashrrev_i32_e32 v49, 31, v48
	s_waitcnt lgkmcnt(0)
	flat_store_dwordx4 v[4:5], v[0:3]
	ds_read_b128 v[0:3], v6
	v_lshl_add_u64 v[4:5], v[20:21], 0, v[184:185]
	v_lshl_add_u64 v[4:5], v[46:47], 1, v[4:5]
	v_lshlrev_b32_e32 v184, 1, v58
	v_add3_u32 v6, v153, v59, v79
	s_waitcnt lgkmcnt(0)
	flat_store_dwordx4 v[4:5], v[0:3]
	ds_read_b128 v[0:3], v7
	v_lshl_add_u64 v[4:5], v[20:21], 0, v[184:185]
	v_lshl_add_u64 v[4:5], v[48:49], 1, v[4:5]
	v_lshlrev_b32_e32 v184, 1, v60
	s_waitcnt lgkmcnt(0)
	flat_store_dwordx4 v[4:5], v[0:3]
	ds_read_b128 v[0:3], v6
	v_lshlrev_b32_e32 v6, 3, v52
	v_lshl_add_u64 v[4:5], v[20:21], 0, v[184:185]
	v_ashrrev_i32_e32 v7, 31, v6
	v_lshl_add_u64 v[4:5], v[6:7], 1, v[4:5]
	s_waitcnt lgkmcnt(0)
	flat_store_dwordx4 v[4:5], v[0:3]
	s_waitcnt lgkmcnt(0)
	s_waitcnt lgkmcnt(0)
	s_barrier
	s_branch .LBB0_355
